# attention: ring slots carried across units, per-unit flag barrier removed (one exchange at phase end), next-unit loads before epilogue; plus hand-written wprep
# baseline (speedup 1.0000x reference)
.Lat_g1:
	s_cmp_lg_u64 s[90:91], 0
	s_cselect_b32 s1, 0, s1
	s_mov_b32 s100, s1
	s_add_i32 s7, s6, s1
	s_mov_b32 s64, 0
	s_movk_i32 s65, 26624
	s_mov_b32 s68, 53248
	s_mov_b32 s69, 112640
	s_mov_b32 s70, 79872
	s_mov_b32 s71, 96256
	v_and_b32_e32 v32, 31, v143
	v_bfe_u32 v33, v143, 5, 1
	v_lshrrev_b32_e32 v34, 6, v143
	v_and_b32_e32 v35, 3, v143
	v_lshlrev_b32_e32 v238, 3, v35
	v_bfe_u32 v35, v143, 2, 2
	v_lshl_add_u32 v238, v35, 6, v238
	v_bfe_u32 v35, v143, 4, 1
	v_lshl_add_u32 v238, v35, 5, v238
	v_lshl_add_u32 v238, v33, 8, v238
	v_lshlrev_b32_e32 v232, 4, v143
	v_add_u32_e32 v239, 0x2000, v232
	v_add_u32_e32 v252, 0x4000, v232
	v_lshlrev_b32_e32 v183, 10, v34
	v_bfe_u32 v35, v143, 2, 1
	v_lshl_add_u32 v183, v35, 9, v183
	v_bfe_u32 v35, v143, 3, 3
	v_lshl_add_u32 v183, v35, 6, v183
	v_and_b32_e32 v35, 3, v143
	v_lshl_add_u32 v183, v35, 4, v183
	v_lshl_add_u32 v39, v34, 5, v32
	v_mul_u32_u24_e32 v133, 0x1440, v39
	v_lshl_add_u32 v133, v33, 3, v133
	v_lshlrev_b32_e32 v134, 11, v39
	v_lshl_add_u32 v134, v33, 3, v134
	s_mov_b32 s101, 0
	s_cmp_ge_i32 s4, s7
	s_cbranch_scc1 .Lat_de_end
	s_cmp_ge_i32 s4, s6
	s_cbranch_scc1 .Lat_de_ctx
	s_mul_i32 s0, s8, s6
	s_add_i32 s0, s0, s4
	s_mul_hi_u32 s1, s0, 0xaaaaaaab
	s_lshr_b32 s1, s1, 7
	s_mul_i32 s32, s1, 192
	s_sub_i32 s32, s0, s32
	s_lshr_b32 s56, s32, 4
	s_and_b32 s32, s32, 15
	s_lshl_b32 s76, s32, 8
	s_lshl_b32 s77, s1, 12
	s_add_i32 s77, s77, s76
	s_mov_b32 s78, 0
	s_mov_b32 s27, 32
	s_branch .Lat_de_ptrs

.Lat_de_ptrs:
	s_mul_i32 s79, s77, 0x1440
	s_lshl_b32 s80, s77, 11
	s_cmp_ge_u32 s56, 6
	s_cbranch_scc1 .Lat_de_gq
	s_mul_i32 s81, s1, 6
	s_add_i32 s81, s81, s56
	s_mul_i32 s81, s81, 4352
	s_add_i32 s82, s81, s76
	s_mul_i32 s82, s82, 192
	s_add_u32 s82, s82, 0x108dd000
	s_add_u32 s10, s50, s82
	s_addc_u32 s11, s51, 0
	s_add_i32 s81, s81, s78
	s_mul_i32 s82, s81, 192
	s_add_u32 s82, s82, 0x12f1d000
	s_add_u32 s16, s50, s82
	s_addc_u32 s17, s51, 0
	s_lshl_b32 s82, s81, 7
	s_add_u32 s82, s82, 0x1555d000
	s_add_u32 s22, s50, s82
	s_addc_u32 s23, s51, 0
	s_lshl_b32 s83, s56, 7
	s_add_u32 s79, s79, s83
	s_add_u32 s79, s79, 97246272
	s_add_u32 s12, s50, s79
	s_addc_u32 s13, s51, 0
	s_add_u32 s80, s80, s83
	s_add_u32 s80, s80, 0x18bd000
	s_add_u32 s14, s50, s80
	s_addc_u32 s15, s51, 0
	s_mov_b32 s101, 1
	v_lshrrev_b32_e32 v172, 6, v143
	v_and_b32_e32 v173, 31, v143
	v_lshl_add_u32 v172, v172, 5, v173
	v_mul_u32_u24_e32 v172, 192, v172
	v_bfe_u32 v173, v143, 5, 1
	v_lshl_add_u32 v172, v173, 4, v172
	global_load_dwordx4 v[184:187], v172, s[10:11] offset:0
	global_load_dwordx4 v[188:191], v172, s[10:11] offset:32
	global_load_dwordx4 v[192:195], v172, s[10:11] offset:64
	global_load_dwordx4 v[196:199], v172, s[10:11] offset:96
	global_load_dwordx4 v[200:203], v172, s[10:11] offset:128
	global_load_dwordx4 v[204:207], v172, s[10:11] offset:160
	global_load_dwordx4 v[208:211], v232, s[16:17]
	global_load_dwordx4 v[212:215], v239, s[16:17]
	global_load_dwordx4 v[216:219], v252, s[16:17]
	global_load_dwordx4 v[220:223], v232, s[22:23]
	global_load_dwordx4 v[224:227], v239, s[22:23]
	s_add_u32 s16, s16, 24576
	s_addc_u32 s17, s17, 0
	s_add_u32 s22, s22, 16384
	s_addc_u32 s23, s23, 0
	global_load_dwordx4 v[144:147], v232, s[16:17]
	global_load_dwordx4 v[148:151], v239, s[16:17]
	global_load_dwordx4 v[152:155], v252, s[16:17]
	s_add_u32 s16, s16, 24576
	s_addc_u32 s17, s17, 0
	s_branch .Lat_de_end
.Lat_de_gq:
	s_add_i32 s56, s56, -6
	s_mul_i32 s81, s1, 6
	s_add_i32 s81, s81, s56
	s_mul_i32 s81, s81, 4352
	s_add_i32 s81, s81, s76
	s_lshl_b32 s81, s81, 7
	s_add_u32 s81, s81, 0x16edd000
	s_add_u32 s10, s50, s81
	s_addc_u32 s11, s51, 0
	s_cmp_ge_u32 s56, 3
	s_cselect_b32 s81, 1, 0
	s_lshl_b32 s82, s1, 1
	s_add_i32 s81, s81, s82
	s_mul_i32 s81, s81, 4352
	s_add_i32 s81, s81, s78
	s_lshl_b32 s81, s81, 7
	s_add_u32 s82, s81, 0x1885d000
	s_add_u32 s16, s50, s82
	s_addc_u32 s17, s51, 0
	s_add_u32 s82, s81, 0x190dd000
	s_add_u32 s22, s50, s82
	s_addc_u32 s23, s51, 0
	s_lshl_b32 s83, s56, 7
	s_add_u32 s79, s79, s83
	s_add_u32 s79, s79, 97247040
	s_add_u32 s12, s50, s79
	s_addc_u32 s13, s51, 0
	s_add_u32 s80, s80, s83
	s_add_u32 s80, s80, 25940736
	s_add_u32 s14, s50, s80
	s_addc_u32 s15, s51, 0
	s_mov_b32 s101, 2
	v_lshrrev_b32_e32 v172, 6, v143
	v_and_b32_e32 v173, 31, v143
	v_lshl_add_u32 v172, v172, 5, v173
	v_mul_u32_u24_e32 v172, 128, v172
	v_bfe_u32 v173, v143, 5, 1
	v_lshl_add_u32 v172, v173, 4, v172
	global_load_dwordx4 v[184:187], v172, s[10:11] offset:0
	global_load_dwordx4 v[188:191], v172, s[10:11] offset:32
	global_load_dwordx4 v[192:195], v172, s[10:11] offset:64
	global_load_dwordx4 v[196:199], v172, s[10:11] offset:96
	global_load_dwordx4 v[208:211], v232, s[16:17]
	global_load_dwordx4 v[212:215], v239, s[16:17]
	global_load_dwordx4 v[220:223], v232, s[22:23]
	global_load_dwordx4 v[224:227], v239, s[22:23]
	s_add_u32 s16, s16, 16384
	s_addc_u32 s17, s17, 0
	s_add_u32 s22, s22, 16384
	s_addc_u32 s23, s23, 0
	global_load_dwordx4 v[144:147], v232, s[16:17]
	global_load_dwordx4 v[148:151], v239, s[16:17]
	s_add_u32 s16, s16, 16384
	s_addc_u32 s17, s17, 0
.Lat_de_end:
	s_cmp_eq_u32 s101, 1
	s_cbranch_scc1 .Lat_m_first
	s_cmp_eq_u32 s101, 2
	s_cbranch_scc1 .Lat_g_first
	s_branch .Lat_done
.Lat_m_pref:
	v_and_b32_e32 v32, 31, v143
	v_bfe_u32 v33, v143, 5, 1
	v_mul_u32_u24_e32 v237, 208, v32
	v_lshl_add_u32 v237, v33, 4, v237
	v_mov_b32_e32 v36, v143
	v_mul_u32_u24_e32 v37, 0xaaab, v36
	v_lshrrev_b32_e32 v37, 19, v37
	v_mul_u32_u24_e32 v38, 12, v37
	v_sub_u32_e32 v38, v36, v38
	v_mul_u32_u24_e32 v37, 208, v37
	v_lshl_add_u32 v179, v38, 4, v37
	v_add_u32_e32 v36, 512, v143
	v_mul_u32_u24_e32 v37, 0xaaab, v36
	v_lshrrev_b32_e32 v37, 19, v37
	v_mul_u32_u24_e32 v38, 12, v37
	v_sub_u32_e32 v38, v36, v38
	v_mul_u32_u24_e32 v37, 208, v37
	v_lshl_add_u32 v181, v38, 4, v37
	v_add_u32_e32 v36, 1024, v143
	v_mul_u32_u24_e32 v37, 0xaaab, v36
	v_lshrrev_b32_e32 v37, 19, v37
	v_mul_u32_u24_e32 v38, 12, v37
	v_sub_u32_e32 v38, v36, v38
	v_mul_u32_u24_e32 v37, 208, v37
	v_lshl_add_u32 v182, v38, 4, v37
	v_mov_b32_e32 v130, 0
	v_mov_b32_e32 v131, 0
	v_mov_b32_e32 v0, 0
	v_mov_b32_e32 v1, 0
	v_mov_b32_e32 v2, 0
	v_mov_b32_e32 v3, 0
	v_mov_b32_e32 v4, 0
	v_mov_b32_e32 v5, 0
	v_mov_b32_e32 v6, 0
	v_mov_b32_e32 v7, 0
	v_mov_b32_e32 v8, 0
	v_mov_b32_e32 v9, 0
	v_mov_b32_e32 v10, 0
	v_mov_b32_e32 v11, 0
	v_mov_b32_e32 v12, 0
	v_mov_b32_e32 v13, 0
	v_mov_b32_e32 v14, 0
	v_mov_b32_e32 v15, 0
	v_mov_b32_e32 v16, 0
	v_mov_b32_e32 v17, 0
	v_mov_b32_e32 v18, 0
	v_mov_b32_e32 v19, 0
	v_mov_b32_e32 v20, 0
	v_mov_b32_e32 v21, 0
	v_mov_b32_e32 v22, 0
	v_mov_b32_e32 v23, 0
	v_mov_b32_e32 v24, 0
	v_mov_b32_e32 v25, 0
	v_mov_b32_e32 v26, 0
	v_mov_b32_e32 v27, 0
	v_mov_b32_e32 v28, 0
	v_mov_b32_e32 v29, 0
	v_mov_b32_e32 v30, 0
	v_mov_b32_e32 v31, 0
	s_waitcnt vmcnt(11)
	v_add_u32_e32 v128, s64, v179
	ds_write_b128 v128, v[208:211]
	v_add_u32_e32 v128, s64, v181
	ds_write_b128 v128, v[212:215]
	v_add_u32_e32 v128, s64, v182
	ds_write_b128 v128, v[216:219]
	v_add_u32_e32 v128, s70, v183
	ds_write_b128 v128, v[220:223]
	ds_write_b128 v128, v[224:227] offset:8192
	global_load_dwordx4 v[208:211], v232, s[16:17]
	global_load_dwordx4 v[212:215], v239, s[16:17]
	global_load_dwordx4 v[216:219], v252, s[16:17]
	global_load_dwordx4 v[220:223], v232, s[22:23]
	global_load_dwordx4 v[224:227], v239, s[22:23]
	s_add_u32 s16, s16, 24576
	s_addc_u32 s17, s17, 0
	s_add_u32 s22, s22, 16384
	s_addc_u32 s23, s23, 0
	s_waitcnt vmcnt(13)
	v_add_u32_e32 v128, s65, v179
	ds_write_b128 v128, v[144:147]
	v_add_u32_e32 v128, s65, v181
	ds_write_b128 v128, v[148:151]
	v_add_u32_e32 v128, s65, v182
	ds_write_b128 v128, v[152:155]
	v_add_u32_e32 v140, s64, v237
	s_waitcnt lgkmcnt(0)
	s_barrier
	s_branch .Lat_m_body
.Lat_m_first:
	v_and_b32_e32 v32, 31, v143
	v_bfe_u32 v33, v143, 5, 1
	v_mul_u32_u24_e32 v237, 208, v32
	v_lshl_add_u32 v237, v33, 4, v237
	v_mov_b32_e32 v36, v143
	v_mul_u32_u24_e32 v37, 0xaaab, v36
	v_lshrrev_b32_e32 v37, 19, v37
	v_mul_u32_u24_e32 v38, 12, v37
	v_sub_u32_e32 v38, v36, v38
	v_mul_u32_u24_e32 v37, 208, v37
	v_lshl_add_u32 v179, v38, 4, v37
	v_add_u32_e32 v36, 512, v143
	v_mul_u32_u24_e32 v37, 0xaaab, v36
	v_lshrrev_b32_e32 v37, 19, v37
	v_mul_u32_u24_e32 v38, 12, v37
	v_sub_u32_e32 v38, v36, v38
	v_mul_u32_u24_e32 v37, 208, v37
	v_lshl_add_u32 v181, v38, 4, v37
	v_add_u32_e32 v36, 1024, v143
	v_mul_u32_u24_e32 v37, 0xaaab, v36
	v_lshrrev_b32_e32 v37, 19, v37
	v_mul_u32_u24_e32 v38, 12, v37
	v_sub_u32_e32 v38, v36, v38
	v_mul_u32_u24_e32 v37, 208, v37
	v_lshl_add_u32 v182, v38, 4, v37
	v_mov_b32_e32 v130, 0
	v_mov_b32_e32 v131, 0
	v_mov_b32_e32 v0, 0
	v_mov_b32_e32 v1, 0
	v_mov_b32_e32 v2, 0
	v_mov_b32_e32 v3, 0
	v_mov_b32_e32 v4, 0
	v_mov_b32_e32 v5, 0
	v_mov_b32_e32 v6, 0
	v_mov_b32_e32 v7, 0
	v_mov_b32_e32 v8, 0
	v_mov_b32_e32 v9, 0
	v_mov_b32_e32 v10, 0
	v_mov_b32_e32 v11, 0
	v_mov_b32_e32 v12, 0
	v_mov_b32_e32 v13, 0
	v_mov_b32_e32 v14, 0
	v_mov_b32_e32 v15, 0
	v_mov_b32_e32 v16, 0
	v_mov_b32_e32 v17, 0
	v_mov_b32_e32 v18, 0
	v_mov_b32_e32 v19, 0
	v_mov_b32_e32 v20, 0
	v_mov_b32_e32 v21, 0
	v_mov_b32_e32 v22, 0
	v_mov_b32_e32 v23, 0
	v_mov_b32_e32 v24, 0
	v_mov_b32_e32 v25, 0
	v_mov_b32_e32 v26, 0
	v_mov_b32_e32 v27, 0
	v_mov_b32_e32 v28, 0
	v_mov_b32_e32 v29, 0
	v_mov_b32_e32 v30, 0
	v_mov_b32_e32 v31, 0
	s_waitcnt vmcnt(3)
	v_add_u32_e32 v128, s64, v179
	ds_write_b128 v128, v[208:211]
	v_add_u32_e32 v128, s64, v181
	ds_write_b128 v128, v[212:215]
	v_add_u32_e32 v128, s64, v182
	ds_write_b128 v128, v[216:219]
	v_add_u32_e32 v128, s70, v183
	ds_write_b128 v128, v[220:223]
	ds_write_b128 v128, v[224:227] offset:8192
	global_load_dwordx4 v[208:211], v232, s[16:17]
	global_load_dwordx4 v[212:215], v239, s[16:17]
	global_load_dwordx4 v[216:219], v252, s[16:17]
	global_load_dwordx4 v[220:223], v232, s[22:23]
	global_load_dwordx4 v[224:227], v239, s[22:23]
	s_add_u32 s16, s16, 24576
	s_addc_u32 s17, s17, 0
	s_add_u32 s22, s22, 16384
	s_addc_u32 s23, s23, 0
	s_waitcnt vmcnt(5)
	v_add_u32_e32 v128, s65, v179
	ds_write_b128 v128, v[144:147]
	v_add_u32_e32 v128, s65, v181
	ds_write_b128 v128, v[148:151]
	v_add_u32_e32 v128, s65, v182
	ds_write_b128 v128, v[152:155]
	v_add_u32_e32 v140, s64, v237
	s_waitcnt lgkmcnt(0)
	s_barrier
.Lat_m_body:
	ds_read_b128 v[144:147], v140 offset:0
	ds_read_b128 v[148:151], v140 offset:32
	ds_read_b128 v[152:155], v140 offset:64
	ds_read_b128 v[156:159], v140 offset:96
	ds_read_b128 v[160:163], v140 offset:128
	ds_read_b128 v[164:167], v140 offset:160
	s_waitcnt lgkmcnt(5)
	v_mfma_f32_32x32x16_bf16 v[32:47], v[144:147], v[184:187], 0
	ds_read_b128 v[168:171], v140 offset:6656
	s_waitcnt lgkmcnt(5)
	v_mfma_f32_32x32x16_bf16 v[32:47], v[148:151], v[188:191], v[32:47]
	ds_read_b128 v[172:175], v140 offset:6688
	s_waitcnt lgkmcnt(5)
	v_mfma_f32_32x32x16_bf16 v[32:47], v[152:155], v[192:195], v[32:47]
	ds_read_b128 v[144:147], v140 offset:6720
	s_waitcnt lgkmcnt(5)
	v_mfma_f32_32x32x16_bf16 v[32:47], v[156:159], v[196:199], v[32:47]
	ds_read_b128 v[148:151], v140 offset:6752
	s_waitcnt lgkmcnt(5)
	v_mfma_f32_32x32x16_bf16 v[32:47], v[160:163], v[200:203], v[32:47]
	ds_read_b128 v[152:155], v140 offset:6784
	s_waitcnt lgkmcnt(5)
	v_mfma_f32_32x32x16_bf16 v[32:47], v[164:167], v[204:207], v[32:47]
	ds_read_b128 v[156:159], v140 offset:6816
	s_waitcnt lgkmcnt(5)
	v_mfma_f32_32x32x16_bf16 v[48:63], v[168:171], v[184:187], 0
	s_waitcnt lgkmcnt(4)
	v_mfma_f32_32x32x16_bf16 v[48:63], v[172:175], v[188:191], v[48:63]
	s_waitcnt lgkmcnt(3)
	v_mfma_f32_32x32x16_bf16 v[48:63], v[144:147], v[192:195], v[48:63]
	s_waitcnt lgkmcnt(2)
	v_mfma_f32_32x32x16_bf16 v[48:63], v[148:151], v[196:199], v[48:63]
	s_waitcnt lgkmcnt(1)
	v_mfma_f32_32x32x16_bf16 v[48:63], v[152:155], v[200:203], v[48:63]
	s_waitcnt lgkmcnt(0)
	v_mfma_f32_32x32x16_bf16 v[48:63], v[156:159], v[204:207], v[48:63]
	s_nop 7
	s_nop 3
	v_add_u32_e32 v140, s64, v237
	v_add_u32_e32 v141, s65, v237
	v_add_u32_e32 v176, s69, v238
	v_add_u32_e32 v177, s70, v238
	ds_read_b128 v[160:163], v140 offset:13312
	ds_read_b128 v[164:167], v140 offset:13344
	ds_read_b128 v[168:171], v140 offset:13376
	ds_read_b128 v[172:175], v140 offset:13408
	ds_read_b128 v[144:147], v140 offset:13440
	ds_read_b128 v[148:151], v140 offset:13472
	s_waitcnt lgkmcnt(5)
	v_mfma_f32_32x32x16_bf16 v[64:79], v[160:163], v[184:187], 0
	ds_read_b128 v[152:155], v140 offset:19968
	v_exp_f32_e32 v32, v32
	v_exp_f32_e32 v33, v33
	v_add_f32_e32 v130, v130, v32
	v_add_f32_e32 v131, v131, v33
	v_cvt_pk_bf16_f32 v96, v32, v33
	v_exp_f32_e32 v34, v34
	v_exp_f32_e32 v35, v35
	s_waitcnt vmcnt(4)
	v_add_u32_e32 v128, s68, v179
	ds_write_b128 v128, v[208:211]
	global_load_dwordx4 v[208:211], v232, s[16:17]
	s_waitcnt lgkmcnt(6)
	v_mfma_f32_32x32x16_bf16 v[64:79], v[164:167], v[188:191], v[64:79]
	ds_read_b128 v[156:159], v140 offset:20000
	v_add_f32_e32 v130, v130, v34
	v_add_f32_e32 v131, v131, v35
	v_cvt_pk_bf16_f32 v97, v34, v35
	v_exp_f32_e32 v36, v36
	v_exp_f32_e32 v37, v37
	v_add_f32_e32 v130, v130, v36
	v_add_f32_e32 v131, v131, v37
	s_waitcnt vmcnt(4)
	v_add_u32_e32 v128, s68, v181
	ds_write_b128 v128, v[212:215]
	global_load_dwordx4 v[212:215], v239, s[16:17]
	s_waitcnt lgkmcnt(7)
	v_mfma_f32_32x32x16_bf16 v[64:79], v[168:171], v[192:195], v[64:79]
	ds_read_b128 v[160:163], v140 offset:20032
	v_cvt_pk_bf16_f32 v98, v36, v37
	v_exp_f32_e32 v38, v38
	v_exp_f32_e32 v39, v39
	v_add_f32_e32 v130, v130, v38
	v_add_f32_e32 v131, v131, v39
	v_cvt_pk_bf16_f32 v99, v38, v39
	s_waitcnt vmcnt(4)
	v_add_u32_e32 v128, s68, v182
	ds_write_b128 v128, v[216:219]
	global_load_dwordx4 v[216:219], v252, s[16:17]
	s_waitcnt lgkmcnt(8)
	v_mfma_f32_32x32x16_bf16 v[64:79], v[172:175], v[196:199], v[64:79]
	ds_read_b128 v[164:167], v140 offset:20064
	v_exp_f32_e32 v40, v40
	v_exp_f32_e32 v41, v41
	v_add_f32_e32 v130, v130, v40
	v_add_f32_e32 v131, v131, v41
	v_cvt_pk_bf16_f32 v100, v40, v41
	v_exp_f32_e32 v42, v42
	v_exp_f32_e32 v43, v43
	s_waitcnt vmcnt(4)
	v_add_u32_e32 v128, s71, v183
	ds_write_b128 v128, v[220:223]
	global_load_dwordx4 v[220:223], v232, s[22:23]
	s_waitcnt lgkmcnt(9)
	v_mfma_f32_32x32x16_bf16 v[64:79], v[144:147], v[200:203], v[64:79]
	ds_read_b128 v[168:171], v140 offset:20096
	v_add_f32_e32 v130, v130, v42
	v_add_f32_e32 v131, v131, v43
	v_cvt_pk_bf16_f32 v101, v42, v43
	v_exp_f32_e32 v44, v44
	v_exp_f32_e32 v45, v45
	v_add_f32_e32 v130, v130, v44
	v_add_f32_e32 v131, v131, v45
	s_waitcnt vmcnt(4)
	v_add_u32_e32 v128, s71, v183
	ds_write_b128 v128, v[224:227] offset:8192
	global_load_dwordx4 v[224:227], v239, s[22:23]
	s_waitcnt lgkmcnt(10)
	v_mfma_f32_32x32x16_bf16 v[64:79], v[148:151], v[204:207], v[64:79]
	ds_read_b128 v[172:175], v140 offset:20128
	v_cvt_pk_bf16_f32 v102, v44, v45
	v_exp_f32_e32 v46, v46
	v_exp_f32_e32 v47, v47
	v_add_f32_e32 v130, v130, v46
	v_add_f32_e32 v131, v131, v47
	v_cvt_pk_bf16_f32 v103, v46, v47
	s_waitcnt lgkmcnt(10)
	v_mfma_f32_32x32x16_bf16 v[80:95], v[152:155], v[184:187], 0
	ds_read_b128 v[144:147], v141 offset:0
	v_exp_f32_e32 v48, v48
	v_exp_f32_e32 v49, v49
	v_add_f32_e32 v130, v130, v48
	v_add_f32_e32 v131, v131, v49
	v_cvt_pk_bf16_f32 v104, v48, v49
	v_exp_f32_e32 v50, v50
	v_exp_f32_e32 v51, v51
	s_waitcnt lgkmcnt(9)
	v_mfma_f32_32x32x16_bf16 v[80:95], v[156:159], v[188:191], v[80:95]
	ds_read_b128 v[148:151], v141 offset:32
	v_add_f32_e32 v130, v130, v50
	v_add_f32_e32 v131, v131, v51
	v_cvt_pk_bf16_f32 v105, v50, v51
	v_exp_f32_e32 v52, v52
	v_exp_f32_e32 v53, v53
	v_add_f32_e32 v130, v130, v52
	v_add_f32_e32 v131, v131, v53
	s_waitcnt lgkmcnt(8)
	v_mfma_f32_32x32x16_bf16 v[80:95], v[160:163], v[192:195], v[80:95]
	ds_read_b128 v[152:155], v141 offset:64
	v_cvt_pk_bf16_f32 v106, v52, v53
	v_exp_f32_e32 v54, v54
	v_exp_f32_e32 v55, v55
	v_add_f32_e32 v130, v130, v54
	v_add_f32_e32 v131, v131, v55
	v_cvt_pk_bf16_f32 v107, v54, v55
	s_waitcnt lgkmcnt(7)
	v_mfma_f32_32x32x16_bf16 v[80:95], v[164:167], v[196:199], v[80:95]
	ds_read_b128 v[156:159], v141 offset:96
	v_exp_f32_e32 v56, v56
	v_exp_f32_e32 v57, v57
	v_add_f32_e32 v130, v130, v56
	v_add_f32_e32 v131, v131, v57
	v_cvt_pk_bf16_f32 v108, v56, v57
	v_exp_f32_e32 v58, v58
	v_exp_f32_e32 v59, v59
	s_waitcnt lgkmcnt(6)
	v_mfma_f32_32x32x16_bf16 v[80:95], v[168:171], v[200:203], v[80:95]
	ds_read_b128 v[160:163], v141 offset:128
	v_add_f32_e32 v130, v130, v58
	v_add_f32_e32 v131, v131, v59
	v_cvt_pk_bf16_f32 v109, v58, v59
	v_exp_f32_e32 v60, v60
	v_exp_f32_e32 v61, v61
	v_add_f32_e32 v130, v130, v60
	v_add_f32_e32 v131, v131, v61
	s_waitcnt lgkmcnt(5)
	v_mfma_f32_32x32x16_bf16 v[80:95], v[172:175], v[204:207], v[80:95]
	ds_read_b128 v[164:167], v141 offset:160
	v_cvt_pk_bf16_f32 v110, v60, v61
	v_exp_f32_e32 v62, v62
	v_exp_f32_e32 v63, v63
	v_add_f32_e32 v130, v130, v62
	v_add_f32_e32 v131, v131, v63
	v_cvt_pk_bf16_f32 v111, v62, v63
	s_add_u32 s16, s16, 24576
	s_addc_u32 s17, s17, 0
	s_add_u32 s22, s22, 16384
	s_addc_u32 s23, s23, 0
	s_waitcnt lgkmcnt(5)
	v_mfma_f32_32x32x16_bf16 v[32:47], v[144:147], v[184:187], 0
	ds_read_b128 v[168:171], v141 offset:6656
	v_exp_f32_e32 v64, v64
	v_exp_f32_e32 v65, v65
	v_add_f32_e32 v130, v130, v64
	v_add_f32_e32 v131, v131, v65
	s_waitcnt lgkmcnt(5)
	v_mfma_f32_32x32x16_bf16 v[32:47], v[148:151], v[188:191], v[32:47]
	ds_read_b128 v[172:175], v141 offset:6688
	v_cvt_pk_bf16_f32 v112, v64, v65
	v_exp_f32_e32 v66, v66
	v_exp_f32_e32 v67, v67
	v_add_f32_e32 v130, v130, v66
	s_waitcnt lgkmcnt(5)
	v_mfma_f32_32x32x16_bf16 v[32:47], v[152:155], v[192:195], v[32:47]
	ds_read_b128 v[144:147], v141 offset:6720
	v_add_f32_e32 v131, v131, v67
	v_cvt_pk_bf16_f32 v113, v66, v67
	v_exp_f32_e32 v68, v68
	v_exp_f32_e32 v69, v69
	s_waitcnt lgkmcnt(5)
	v_mfma_f32_32x32x16_bf16 v[32:47], v[156:159], v[196:199], v[32:47]
	ds_read_b128 v[148:151], v141 offset:6752
	v_add_f32_e32 v130, v130, v68
	v_add_f32_e32 v131, v131, v69
	v_cvt_pk_bf16_f32 v114, v68, v69
	v_exp_f32_e32 v70, v70
	s_waitcnt lgkmcnt(5)
	v_mfma_f32_32x32x16_bf16 v[32:47], v[160:163], v[200:203], v[32:47]
	ds_read_b128 v[152:155], v141 offset:6784
	v_exp_f32_e32 v71, v71
	v_add_f32_e32 v130, v130, v70
	v_add_f32_e32 v131, v131, v71
	v_cvt_pk_bf16_f32 v115, v70, v71
	s_waitcnt lgkmcnt(5)
	v_mfma_f32_32x32x16_bf16 v[32:47], v[164:167], v[204:207], v[32:47]
	ds_read_b128 v[156:159], v141 offset:6816
	v_exp_f32_e32 v72, v72
	v_exp_f32_e32 v73, v73
	v_add_f32_e32 v130, v130, v72
	v_add_f32_e32 v131, v131, v73
	s_waitcnt lgkmcnt(5)
	v_mfma_f32_32x32x16_bf16 v[48:63], v[168:171], v[184:187], 0
	ds_read_b64_tr_b16 v[160:161], v177 offset:0
	ds_read_b64_tr_b16 v[162:163], v177 offset:1024
	v_cvt_pk_bf16_f32 v116, v72, v73
	v_exp_f32_e32 v74, v74
	v_exp_f32_e32 v75, v75
	v_add_f32_e32 v130, v130, v74
	s_waitcnt lgkmcnt(6)
	v_mfma_f32_32x32x16_bf16 v[48:63], v[172:175], v[188:191], v[48:63]
	ds_read_b64_tr_b16 v[164:165], v177 offset:512
	ds_read_b64_tr_b16 v[166:167], v177 offset:1536
	v_add_f32_e32 v131, v131, v75
	v_cvt_pk_bf16_f32 v117, v74, v75
	v_exp_f32_e32 v76, v76
	v_exp_f32_e32 v77, v77
	s_waitcnt lgkmcnt(7)
	v_mfma_f32_32x32x16_bf16 v[48:63], v[144:147], v[192:195], v[48:63]
	ds_read_b64_tr_b16 v[168:169], v177 offset:2048
	ds_read_b64_tr_b16 v[170:171], v177 offset:3072
	v_add_f32_e32 v130, v130, v76
	v_add_f32_e32 v131, v131, v77
	v_cvt_pk_bf16_f32 v118, v76, v77
	v_exp_f32_e32 v78, v78
	s_waitcnt lgkmcnt(8)
	v_mfma_f32_32x32x16_bf16 v[48:63], v[148:151], v[196:199], v[48:63]
	ds_read_b64_tr_b16 v[172:173], v177 offset:2560
	ds_read_b64_tr_b16 v[174:175], v177 offset:3584
	v_exp_f32_e32 v79, v79
	v_add_f32_e32 v130, v130, v78
	v_add_f32_e32 v131, v131, v79
	v_cvt_pk_bf16_f32 v119, v78, v79
	s_waitcnt lgkmcnt(9)
	v_mfma_f32_32x32x16_bf16 v[48:63], v[152:155], v[200:203], v[48:63]
	ds_read_b64_tr_b16 v[144:145], v177 offset:4096
	ds_read_b64_tr_b16 v[146:147], v177 offset:5120
	v_exp_f32_e32 v80, v80
	v_exp_f32_e32 v81, v81
	v_add_f32_e32 v130, v130, v80
	v_add_f32_e32 v131, v131, v81
	s_waitcnt lgkmcnt(10)
	v_mfma_f32_32x32x16_bf16 v[48:63], v[156:159], v[204:207], v[48:63]
	ds_read_b64_tr_b16 v[148:149], v177 offset:4608
	ds_read_b64_tr_b16 v[150:151], v177 offset:5632
	v_cvt_pk_bf16_f32 v120, v80, v81
	v_exp_f32_e32 v82, v82
	v_exp_f32_e32 v83, v83
	v_add_f32_e32 v130, v130, v82
	s_waitcnt lgkmcnt(10)
	v_mfma_f32_32x32x16_bf16 v[0:15], v[160:163], v[96:99], v[0:15]
	ds_read_b64_tr_b16 v[152:153], v177 offset:6144
	ds_read_b64_tr_b16 v[154:155], v177 offset:7168
	v_add_f32_e32 v131, v131, v83
	v_cvt_pk_bf16_f32 v121, v82, v83
	v_exp_f32_e32 v84, v84
	v_exp_f32_e32 v85, v85
	s_waitcnt lgkmcnt(10)
	v_mfma_f32_32x32x16_bf16 v[16:31], v[164:167], v[96:99], v[16:31]
	ds_read_b64_tr_b16 v[156:157], v177 offset:6656
	ds_read_b64_tr_b16 v[158:159], v177 offset:7680
	v_add_f32_e32 v130, v130, v84
	v_add_f32_e32 v131, v131, v85
	v_cvt_pk_bf16_f32 v122, v84, v85
	v_exp_f32_e32 v86, v86
	s_waitcnt lgkmcnt(10)
	v_mfma_f32_32x32x16_bf16 v[0:15], v[168:171], v[100:103], v[0:15]
	ds_read_b128 v[160:163], v141 offset:13312
	v_exp_f32_e32 v87, v87
	v_add_f32_e32 v130, v130, v86
	v_add_f32_e32 v131, v131, v87
	v_cvt_pk_bf16_f32 v123, v86, v87
	s_waitcnt lgkmcnt(9)
	v_mfma_f32_32x32x16_bf16 v[16:31], v[172:175], v[100:103], v[16:31]
	ds_read_b128 v[164:167], v141 offset:13344
	v_exp_f32_e32 v88, v88
	v_exp_f32_e32 v89, v89
	v_add_f32_e32 v130, v130, v88
	v_add_f32_e32 v131, v131, v89
	s_waitcnt lgkmcnt(8)
	v_mfma_f32_32x32x16_bf16 v[0:15], v[144:147], v[104:107], v[0:15]
	ds_read_b128 v[168:171], v141 offset:13376
	v_cvt_pk_bf16_f32 v124, v88, v89
	v_exp_f32_e32 v90, v90
	v_exp_f32_e32 v91, v91
	v_add_f32_e32 v130, v130, v90
	s_waitcnt lgkmcnt(7)
	v_mfma_f32_32x32x16_bf16 v[16:31], v[148:151], v[104:107], v[16:31]
	ds_read_b128 v[172:175], v141 offset:13408
	v_add_f32_e32 v131, v131, v91
	v_cvt_pk_bf16_f32 v125, v90, v91
	v_exp_f32_e32 v92, v92
	v_exp_f32_e32 v93, v93
	s_waitcnt lgkmcnt(6)
	v_mfma_f32_32x32x16_bf16 v[0:15], v[152:155], v[108:111], v[0:15]
	ds_read_b128 v[144:147], v141 offset:13440
	v_add_f32_e32 v130, v130, v92
	v_add_f32_e32 v131, v131, v93
	v_cvt_pk_bf16_f32 v126, v92, v93
	v_exp_f32_e32 v94, v94
	s_waitcnt lgkmcnt(5)
	v_mfma_f32_32x32x16_bf16 v[16:31], v[156:159], v[108:111], v[16:31]
	ds_read_b128 v[148:151], v141 offset:13472
	v_exp_f32_e32 v95, v95
	v_add_f32_e32 v130, v130, v94
	v_add_f32_e32 v131, v131, v95
	v_cvt_pk_bf16_f32 v127, v94, v95
	s_mov_b32 s0, s64
	s_mov_b32 s64, s65
	s_mov_b32 s65, s68
	s_mov_b32 s68, s0
	s_mov_b32 s0, s69
	s_mov_b32 s69, s70
	s_mov_b32 s70, s71
	s_mov_b32 s71, s0
	s_barrier
	s_cmp_eq_u32 s27, 0
	s_cbranch_scc1 .Lat_m_last

.Lat_m_last:
	v_add_u32_e32 v140, s64, v237
	v_add_u32_e32 v141, s65, v237
	v_add_u32_e32 v176, s69, v238
	v_add_u32_e32 v177, s70, v238
	s_waitcnt lgkmcnt(5)
	v_mfma_f32_32x32x16_bf16 v[64:79], v[160:163], v[184:187], 0
	ds_read_b128 v[152:155], v140 offset:19968
	v_exp_f32_e32 v32, v32
	v_exp_f32_e32 v33, v33
	v_add_f32_e32 v130, v130, v32
	v_add_f32_e32 v131, v131, v33
	s_waitcnt lgkmcnt(5)
	v_mfma_f32_32x32x16_bf16 v[64:79], v[164:167], v[188:191], v[64:79]
	ds_read_b128 v[156:159], v140 offset:20000
	v_cvt_pk_bf16_f32 v96, v32, v33
	v_exp_f32_e32 v34, v34
	v_exp_f32_e32 v35, v35
	v_add_f32_e32 v130, v130, v34
	s_waitcnt lgkmcnt(5)
	v_mfma_f32_32x32x16_bf16 v[64:79], v[168:171], v[192:195], v[64:79]
	ds_read_b128 v[160:163], v140 offset:20032
	v_add_f32_e32 v131, v131, v35
	v_cvt_pk_bf16_f32 v97, v34, v35
	v_exp_f32_e32 v36, v36
	v_exp_f32_e32 v37, v37
	s_waitcnt lgkmcnt(5)
	v_mfma_f32_32x32x16_bf16 v[64:79], v[172:175], v[196:199], v[64:79]
	ds_read_b128 v[164:167], v140 offset:20064
	v_add_f32_e32 v130, v130, v36
	v_add_f32_e32 v131, v131, v37
	v_cvt_pk_bf16_f32 v98, v36, v37
	v_exp_f32_e32 v38, v38
	s_waitcnt lgkmcnt(5)
	v_mfma_f32_32x32x16_bf16 v[64:79], v[144:147], v[200:203], v[64:79]
	ds_read_b128 v[168:171], v140 offset:20096
	v_exp_f32_e32 v39, v39
	v_add_f32_e32 v130, v130, v38
	v_add_f32_e32 v131, v131, v39
	v_cvt_pk_bf16_f32 v99, v38, v39
	s_waitcnt lgkmcnt(5)
	v_mfma_f32_32x32x16_bf16 v[64:79], v[148:151], v[204:207], v[64:79]
	ds_read_b128 v[172:175], v140 offset:20128
	v_exp_f32_e32 v40, v40
	v_exp_f32_e32 v41, v41
	v_add_f32_e32 v130, v130, v40
	v_add_f32_e32 v131, v131, v41
	s_waitcnt lgkmcnt(5)
	v_mfma_f32_32x32x16_bf16 v[80:95], v[152:155], v[184:187], 0
	ds_read_b64_tr_b16 v[144:145], v176 offset:8192
	ds_read_b64_tr_b16 v[146:147], v176 offset:9216
	v_cvt_pk_bf16_f32 v100, v40, v41
	v_exp_f32_e32 v42, v42
	v_exp_f32_e32 v43, v43
	v_add_f32_e32 v130, v130, v42
	s_waitcnt lgkmcnt(6)
	v_mfma_f32_32x32x16_bf16 v[80:95], v[156:159], v[188:191], v[80:95]
	ds_read_b64_tr_b16 v[148:149], v176 offset:8704
	ds_read_b64_tr_b16 v[150:151], v176 offset:9728
	v_add_f32_e32 v131, v131, v43
	v_cvt_pk_bf16_f32 v101, v42, v43
	v_exp_f32_e32 v44, v44
	v_exp_f32_e32 v45, v45
	s_waitcnt lgkmcnt(7)
	v_mfma_f32_32x32x16_bf16 v[80:95], v[160:163], v[192:195], v[80:95]
	ds_read_b64_tr_b16 v[152:153], v176 offset:10240
	ds_read_b64_tr_b16 v[154:155], v176 offset:11264
	v_add_f32_e32 v130, v130, v44
	v_add_f32_e32 v131, v131, v45
	v_cvt_pk_bf16_f32 v102, v44, v45
	v_exp_f32_e32 v46, v46
	s_waitcnt lgkmcnt(8)
	v_mfma_f32_32x32x16_bf16 v[80:95], v[164:167], v[196:199], v[80:95]
	ds_read_b64_tr_b16 v[156:157], v176 offset:10752
	ds_read_b64_tr_b16 v[158:159], v176 offset:11776
	v_exp_f32_e32 v47, v47
	v_add_f32_e32 v130, v130, v46
	v_add_f32_e32 v131, v131, v47
	v_cvt_pk_bf16_f32 v103, v46, v47
	s_waitcnt lgkmcnt(9)
	v_mfma_f32_32x32x16_bf16 v[80:95], v[168:171], v[200:203], v[80:95]
	ds_read_b64_tr_b16 v[160:161], v176 offset:12288
	ds_read_b64_tr_b16 v[162:163], v176 offset:13312
	v_exp_f32_e32 v48, v48
	v_exp_f32_e32 v49, v49
	v_add_f32_e32 v130, v130, v48
	v_add_f32_e32 v131, v131, v49
	s_waitcnt lgkmcnt(10)
	v_mfma_f32_32x32x16_bf16 v[80:95], v[172:175], v[204:207], v[80:95]
	ds_read_b64_tr_b16 v[164:165], v176 offset:12800
	ds_read_b64_tr_b16 v[166:167], v176 offset:13824
	v_cvt_pk_bf16_f32 v104, v48, v49
	v_exp_f32_e32 v50, v50
	v_exp_f32_e32 v51, v51
	v_add_f32_e32 v130, v130, v50
	s_waitcnt lgkmcnt(10)
	v_mfma_f32_32x32x16_bf16 v[0:15], v[144:147], v[112:115], v[0:15]
	ds_read_b64_tr_b16 v[168:169], v176 offset:14336
	ds_read_b64_tr_b16 v[170:171], v176 offset:15360
	v_add_f32_e32 v131, v131, v51
	v_cvt_pk_bf16_f32 v105, v50, v51
	v_exp_f32_e32 v52, v52
	v_exp_f32_e32 v53, v53
	s_waitcnt lgkmcnt(10)
	v_mfma_f32_32x32x16_bf16 v[16:31], v[148:151], v[112:115], v[16:31]
	ds_read_b64_tr_b16 v[172:173], v176 offset:14848
	ds_read_b64_tr_b16 v[174:175], v176 offset:15872
	v_add_f32_e32 v130, v130, v52
	v_add_f32_e32 v131, v131, v53
	v_cvt_pk_bf16_f32 v106, v52, v53
	v_exp_f32_e32 v54, v54
	s_waitcnt lgkmcnt(10)
	v_mfma_f32_32x32x16_bf16 v[0:15], v[152:155], v[116:119], v[0:15]
	ds_read_b64_tr_b16 v[144:145], v177 offset:0
	ds_read_b64_tr_b16 v[146:147], v177 offset:1024
	v_exp_f32_e32 v55, v55
	v_add_f32_e32 v130, v130, v54
	v_add_f32_e32 v131, v131, v55
	v_cvt_pk_bf16_f32 v107, v54, v55
	s_waitcnt lgkmcnt(10)
	v_mfma_f32_32x32x16_bf16 v[16:31], v[156:159], v[116:119], v[16:31]
	ds_read_b64_tr_b16 v[148:149], v177 offset:512
	ds_read_b64_tr_b16 v[150:151], v177 offset:1536
	v_exp_f32_e32 v56, v56
	v_exp_f32_e32 v57, v57
	v_add_f32_e32 v130, v130, v56
	v_add_f32_e32 v131, v131, v57
	s_waitcnt lgkmcnt(10)
	v_mfma_f32_32x32x16_bf16 v[0:15], v[160:163], v[120:123], v[0:15]
	ds_read_b64_tr_b16 v[152:153], v177 offset:2048
	ds_read_b64_tr_b16 v[154:155], v177 offset:3072
	v_cvt_pk_bf16_f32 v108, v56, v57
	v_exp_f32_e32 v58, v58
	v_exp_f32_e32 v59, v59
	v_add_f32_e32 v130, v130, v58
	s_waitcnt lgkmcnt(10)
	v_mfma_f32_32x32x16_bf16 v[16:31], v[164:167], v[120:123], v[16:31]
	ds_read_b64_tr_b16 v[156:157], v177 offset:2560
	ds_read_b64_tr_b16 v[158:159], v177 offset:3584
	v_add_f32_e32 v131, v131, v59
	v_cvt_pk_bf16_f32 v109, v58, v59
	v_exp_f32_e32 v60, v60
	v_exp_f32_e32 v61, v61
	s_waitcnt lgkmcnt(10)
	v_mfma_f32_32x32x16_bf16 v[0:15], v[168:171], v[124:127], v[0:15]
	ds_read_b64_tr_b16 v[160:161], v177 offset:4096
	ds_read_b64_tr_b16 v[162:163], v177 offset:5120
	v_add_f32_e32 v130, v130, v60
	v_add_f32_e32 v131, v131, v61
	v_cvt_pk_bf16_f32 v110, v60, v61
	v_exp_f32_e32 v62, v62
	s_waitcnt lgkmcnt(10)
	v_mfma_f32_32x32x16_bf16 v[16:31], v[172:175], v[124:127], v[16:31]
	ds_read_b64_tr_b16 v[164:165], v177 offset:4608
	ds_read_b64_tr_b16 v[166:167], v177 offset:5632
	v_exp_f32_e32 v63, v63
	v_add_f32_e32 v130, v130, v62
	v_add_f32_e32 v131, v131, v63
	v_cvt_pk_bf16_f32 v111, v62, v63
	s_waitcnt lgkmcnt(10)
	v_mfma_f32_32x32x16_bf16 v[0:15], v[144:147], v[96:99], v[0:15]
	ds_read_b64_tr_b16 v[168:169], v177 offset:6144
	ds_read_b64_tr_b16 v[170:171], v177 offset:7168
	v_exp_f32_e32 v64, v64
	v_exp_f32_e32 v65, v65
	v_add_f32_e32 v130, v130, v64
	v_add_f32_e32 v131, v131, v65
	v_cvt_pk_bf16_f32 v112, v64, v65
	v_exp_f32_e32 v66, v66
	v_exp_f32_e32 v67, v67
	v_add_f32_e32 v130, v130, v66
	v_add_f32_e32 v131, v131, v67
	v_cvt_pk_bf16_f32 v113, v66, v67
	global_load_dwordx2 v[32:33], v133, s[12:13] offset:0
	s_waitcnt lgkmcnt(10)
	v_mfma_f32_32x32x16_bf16 v[16:31], v[148:151], v[96:99], v[16:31]
	ds_read_b64_tr_b16 v[172:173], v177 offset:6656
	ds_read_b64_tr_b16 v[174:175], v177 offset:7680
	v_exp_f32_e32 v68, v68
	v_exp_f32_e32 v69, v69
	v_add_f32_e32 v130, v130, v68
	v_add_f32_e32 v131, v131, v69
	v_cvt_pk_bf16_f32 v114, v68, v69
	v_exp_f32_e32 v70, v70
	v_exp_f32_e32 v71, v71
	v_add_f32_e32 v130, v130, v70
	v_add_f32_e32 v131, v131, v71
	v_cvt_pk_bf16_f32 v115, v70, v71
	global_load_dwordx2 v[34:35], v133, s[12:13] offset:64
	s_waitcnt lgkmcnt(10)
	v_mfma_f32_32x32x16_bf16 v[0:15], v[152:155], v[100:103], v[0:15]
	v_exp_f32_e32 v72, v72
	v_exp_f32_e32 v73, v73
	v_add_f32_e32 v130, v130, v72
	v_add_f32_e32 v131, v131, v73
	v_cvt_pk_bf16_f32 v116, v72, v73
	v_exp_f32_e32 v74, v74
	v_exp_f32_e32 v75, v75
	v_add_f32_e32 v130, v130, v74
	v_add_f32_e32 v131, v131, v75
	v_cvt_pk_bf16_f32 v117, v74, v75
	global_load_dwordx2 v[36:37], v133, s[12:13] offset:16
	s_waitcnt lgkmcnt(8)
	v_mfma_f32_32x32x16_bf16 v[16:31], v[156:159], v[100:103], v[16:31]
	v_exp_f32_e32 v76, v76
	v_exp_f32_e32 v77, v77
	v_add_f32_e32 v130, v130, v76
	v_add_f32_e32 v131, v131, v77
	v_cvt_pk_bf16_f32 v118, v76, v77
	v_exp_f32_e32 v78, v78
	v_exp_f32_e32 v79, v79
	v_add_f32_e32 v130, v130, v78
	v_add_f32_e32 v131, v131, v79
	v_cvt_pk_bf16_f32 v119, v78, v79
	global_load_dwordx2 v[38:39], v133, s[12:13] offset:80
	s_waitcnt lgkmcnt(6)
	v_mfma_f32_32x32x16_bf16 v[0:15], v[160:163], v[104:107], v[0:15]
	v_exp_f32_e32 v80, v80
	v_exp_f32_e32 v81, v81
	v_add_f32_e32 v130, v130, v80
	v_add_f32_e32 v131, v131, v81
	v_cvt_pk_bf16_f32 v120, v80, v81
	v_exp_f32_e32 v82, v82
	v_exp_f32_e32 v83, v83
	v_add_f32_e32 v130, v130, v82
	v_add_f32_e32 v131, v131, v83
	v_cvt_pk_bf16_f32 v121, v82, v83
	global_load_dwordx2 v[40:41], v133, s[12:13] offset:32
	s_waitcnt lgkmcnt(4)
	v_mfma_f32_32x32x16_bf16 v[16:31], v[164:167], v[104:107], v[16:31]
	v_exp_f32_e32 v84, v84
	v_exp_f32_e32 v85, v85
	v_add_f32_e32 v130, v130, v84
	v_add_f32_e32 v131, v131, v85
	v_cvt_pk_bf16_f32 v122, v84, v85
	v_exp_f32_e32 v86, v86
	v_exp_f32_e32 v87, v87
	v_add_f32_e32 v130, v130, v86
	v_add_f32_e32 v131, v131, v87
	v_cvt_pk_bf16_f32 v123, v86, v87
	global_load_dwordx2 v[42:43], v133, s[12:13] offset:96
	s_waitcnt lgkmcnt(2)
	v_mfma_f32_32x32x16_bf16 v[0:15], v[168:171], v[108:111], v[0:15]
	v_exp_f32_e32 v88, v88
	v_exp_f32_e32 v89, v89
	v_add_f32_e32 v130, v130, v88
	v_add_f32_e32 v131, v131, v89
	v_cvt_pk_bf16_f32 v124, v88, v89
	v_exp_f32_e32 v90, v90
	v_exp_f32_e32 v91, v91
	v_add_f32_e32 v130, v130, v90
	v_add_f32_e32 v131, v131, v91
	v_cvt_pk_bf16_f32 v125, v90, v91
	global_load_dwordx2 v[44:45], v133, s[12:13] offset:48
	s_waitcnt lgkmcnt(0)
	v_mfma_f32_32x32x16_bf16 v[16:31], v[172:175], v[108:111], v[16:31]
	v_exp_f32_e32 v92, v92
	v_exp_f32_e32 v93, v93
	v_add_f32_e32 v130, v130, v92
	v_add_f32_e32 v131, v131, v93
	v_cvt_pk_bf16_f32 v126, v92, v93
	v_exp_f32_e32 v94, v94
	v_exp_f32_e32 v95, v95
	v_add_f32_e32 v130, v130, v94
	v_add_f32_e32 v131, v131, v95
	v_cvt_pk_bf16_f32 v127, v94, v95
	global_load_dwordx2 v[46:47], v133, s[12:13] offset:112
	v_add_u32_e32 v176, s70, v238
	ds_read_b64_tr_b16 v[144:145], v176 offset:8192
	ds_read_b64_tr_b16 v[146:147], v176 offset:9216
	ds_read_b64_tr_b16 v[148:149], v176 offset:8704
	ds_read_b64_tr_b16 v[150:151], v176 offset:9728
	ds_read_b64_tr_b16 v[152:153], v176 offset:10240
	ds_read_b64_tr_b16 v[154:155], v176 offset:11264
	ds_read_b64_tr_b16 v[156:157], v176 offset:10752
	ds_read_b64_tr_b16 v[158:159], v176 offset:11776
	ds_read_b64_tr_b16 v[160:161], v176 offset:12288
	ds_read_b64_tr_b16 v[162:163], v176 offset:13312
	ds_read_b64_tr_b16 v[164:165], v176 offset:12800
	ds_read_b64_tr_b16 v[166:167], v176 offset:13824
	s_waitcnt lgkmcnt(10)
	v_mfma_f32_32x32x16_bf16 v[0:15], v[144:147], v[112:115], v[0:15]
	ds_read_b64_tr_b16 v[168:169], v176 offset:14336
	ds_read_b64_tr_b16 v[170:171], v176 offset:15360
	s_waitcnt lgkmcnt(10)
	v_mfma_f32_32x32x16_bf16 v[16:31], v[148:151], v[112:115], v[16:31]
	ds_read_b64_tr_b16 v[172:173], v176 offset:14848
	ds_read_b64_tr_b16 v[174:175], v176 offset:15872
	s_waitcnt lgkmcnt(10)
	v_mfma_f32_32x32x16_bf16 v[0:15], v[152:155], v[116:119], v[0:15]
	s_waitcnt lgkmcnt(8)
	v_mfma_f32_32x32x16_bf16 v[16:31], v[156:159], v[116:119], v[16:31]
	s_waitcnt lgkmcnt(6)
	v_mfma_f32_32x32x16_bf16 v[0:15], v[160:163], v[120:123], v[0:15]
	s_waitcnt lgkmcnt(4)
	v_mfma_f32_32x32x16_bf16 v[16:31], v[164:167], v[120:123], v[16:31]
	s_waitcnt lgkmcnt(2)
	v_mfma_f32_32x32x16_bf16 v[0:15], v[168:171], v[124:127], v[0:15]
	s_waitcnt lgkmcnt(0)
	v_mfma_f32_32x32x16_bf16 v[16:31], v[172:175], v[124:127], v[16:31]
	s_mov_b32 s0, s64
	s_mov_b32 s64, s65
	s_mov_b32 s65, s68
	s_mov_b32 s68, s0
	s_mov_b32 s0, s69
	s_mov_b32 s69, s70
	s_mov_b32 s70, s71
	s_mov_b32 s71, s0
	s_waitcnt vmcnt(0)
	s_mov_b64 s[30:31], s[14:15]
	s_add_i32 s4, s4, s5
	s_mov_b32 s101, 0
	s_cmp_ge_i32 s4, s7
	s_cbranch_scc1 .Lat_dm_end
	s_cmp_ge_i32 s4, s6
	s_cbranch_scc1 .Lat_dm_ctx
	s_mul_i32 s0, s8, s6
	s_add_i32 s0, s0, s4
	s_mul_hi_u32 s1, s0, 0xaaaaaaab
	s_lshr_b32 s1, s1, 7
	s_mul_i32 s32, s1, 192
	s_sub_i32 s32, s0, s32
	s_lshr_b32 s56, s32, 4
	s_and_b32 s32, s32, 15
	s_lshl_b32 s76, s32, 8
	s_lshl_b32 s77, s1, 12
	s_add_i32 s77, s77, s76
	s_mov_b32 s78, 0
	s_mov_b32 s27, 32
	s_branch .Lat_dm_ptrs

.Lat_dm_end:
	v_add_f32_e32 v135, v130, v131
	v_mov_b32_e32 v128, v135
	s_nop 1
	v_permlane32_swap_b32_e32 v135, v128
	s_nop 1
	v_add_f32_e32 v135, v135, v128
	s_mov_b32 s0, 0x7149f2ca
	v_cmp_lt_f32_e32 vcc, 0xda24260, v135
	v_cmp_gt_f32_e64 s[76:77], s0, v135
	s_nop 1
	s_and_b64 s[76:77], s[76:77], vcc
	s_andn2_b64 s[76:77], exec, s[76:77]
	s_cmp_lg_u64 s[76:77], 0
	s_cselect_b32 s0, 1, 0
	s_and_b32 s1, s9, 31
	s_lshl_b32 s1, s0, s1
	s_or_b32 s26, s26, s1
	v_rcp_f32_e32 v136, v135
	s_nop 0
	v_fma_f32 v128, -v135, v136, 1.0
	v_fma_f32 v136, v136, v128, v136
	s_add_i32 s9, s9, 1
	s_mov_b32 s0, 0xbfb8aa3b
	v_lshlrev_b32_e32 v56, 16, v32
	v_and_b32_e32 v57, 0xffff0000, v32
	v_lshlrev_b32_e32 v58, 16, v33
	v_and_b32_e32 v59, 0xffff0000, v33
	v_mul_f32_e32 v62, s0, v56
	v_mul_f32_e32 v63, s0, v57
	v_mul_f32_e32 v48, s0, v58
	v_mul_f32_e32 v49, s0, v59
	v_exp_f32_e32 v62, v62
	v_exp_f32_e32 v63, v63
	v_exp_f32_e32 v48, v48
	v_exp_f32_e32 v49, v49
	s_nop 0
	v_add_f32_e32 v62, 1.0, v62
	v_add_f32_e32 v63, 1.0, v63
	v_add_f32_e32 v48, 1.0, v48
	v_add_f32_e32 v49, 1.0, v49
	v_rcp_f32_e32 v62, v62
	v_rcp_f32_e32 v63, v63
	v_rcp_f32_e32 v48, v48
	v_rcp_f32_e32 v49, v49
	s_nop 0
	v_mul_f32_e32 v56, v56, v62
	v_mul_f32_e32 v57, v57, v63
	v_mul_f32_e32 v58, v58, v48
	v_mul_f32_e32 v59, v59, v49
	v_mul_f32_e32 v62, v0, v136
	v_mul_f32_e32 v63, v1, v136
	v_mul_f32_e32 v48, v2, v136
	v_mul_f32_e32 v49, v3, v136
	v_mul_f32_e32 v62, v62, v56
	v_mul_f32_e32 v63, v63, v57
	v_mul_f32_e32 v48, v48, v58
	v_mul_f32_e32 v49, v49, v59
	v_cvt_pk_bf16_f32 v60, v62, v63
	v_cvt_pk_bf16_f32 v61, v48, v49
	global_store_dwordx2 v134, v[60:61], s[30:31] offset:0
	s_nop 0
	v_lshlrev_b32_e32 v56, 16, v34
	v_and_b32_e32 v57, 0xffff0000, v34
	v_lshlrev_b32_e32 v58, 16, v35
	v_and_b32_e32 v59, 0xffff0000, v35
	v_mul_f32_e32 v62, s0, v56
	v_mul_f32_e32 v63, s0, v57
	v_mul_f32_e32 v48, s0, v58
	v_mul_f32_e32 v49, s0, v59
	v_exp_f32_e32 v62, v62
	v_exp_f32_e32 v63, v63
	v_exp_f32_e32 v48, v48
	v_exp_f32_e32 v49, v49
	s_nop 0
	v_add_f32_e32 v62, 1.0, v62
	v_add_f32_e32 v63, 1.0, v63
	v_add_f32_e32 v48, 1.0, v48
	v_add_f32_e32 v49, 1.0, v49
	v_rcp_f32_e32 v62, v62
	v_rcp_f32_e32 v63, v63
	v_rcp_f32_e32 v48, v48
	v_rcp_f32_e32 v49, v49
	s_nop 0
	v_mul_f32_e32 v56, v56, v62
	v_mul_f32_e32 v57, v57, v63
	v_mul_f32_e32 v58, v58, v48
	v_mul_f32_e32 v59, v59, v49
	v_mul_f32_e32 v62, v16, v136
	v_mul_f32_e32 v63, v17, v136
	v_mul_f32_e32 v48, v18, v136
	v_mul_f32_e32 v49, v19, v136
	v_mul_f32_e32 v62, v62, v56
	v_mul_f32_e32 v63, v63, v57
	v_mul_f32_e32 v48, v48, v58
	v_mul_f32_e32 v49, v49, v59
	v_cvt_pk_bf16_f32 v60, v62, v63
	v_cvt_pk_bf16_f32 v61, v48, v49
	global_store_dwordx2 v134, v[60:61], s[30:31] offset:64
	s_nop 0
	v_lshlrev_b32_e32 v56, 16, v36
	v_and_b32_e32 v57, 0xffff0000, v36
	v_lshlrev_b32_e32 v58, 16, v37
	v_and_b32_e32 v59, 0xffff0000, v37
	v_mul_f32_e32 v62, s0, v56
	v_mul_f32_e32 v63, s0, v57
	v_mul_f32_e32 v48, s0, v58
	v_mul_f32_e32 v49, s0, v59
	v_exp_f32_e32 v62, v62
	v_exp_f32_e32 v63, v63
	v_exp_f32_e32 v48, v48
	v_exp_f32_e32 v49, v49
	s_nop 0
	v_add_f32_e32 v62, 1.0, v62
	v_add_f32_e32 v63, 1.0, v63
	v_add_f32_e32 v48, 1.0, v48
	v_add_f32_e32 v49, 1.0, v49
	v_rcp_f32_e32 v62, v62
	v_rcp_f32_e32 v63, v63
	v_rcp_f32_e32 v48, v48
	v_rcp_f32_e32 v49, v49
	s_nop 0
	v_mul_f32_e32 v56, v56, v62
	v_mul_f32_e32 v57, v57, v63
	v_mul_f32_e32 v58, v58, v48
	v_mul_f32_e32 v59, v59, v49
	v_mul_f32_e32 v62, v4, v136
	v_mul_f32_e32 v63, v5, v136
	v_mul_f32_e32 v48, v6, v136
	v_mul_f32_e32 v49, v7, v136
	v_mul_f32_e32 v62, v62, v56
	v_mul_f32_e32 v63, v63, v57
	v_mul_f32_e32 v48, v48, v58
	v_mul_f32_e32 v49, v49, v59
	v_cvt_pk_bf16_f32 v60, v62, v63
	v_cvt_pk_bf16_f32 v61, v48, v49
	global_store_dwordx2 v134, v[60:61], s[30:31] offset:16
	s_nop 0
	v_lshlrev_b32_e32 v56, 16, v38
	v_and_b32_e32 v57, 0xffff0000, v38
	v_lshlrev_b32_e32 v58, 16, v39
	v_and_b32_e32 v59, 0xffff0000, v39
	v_mul_f32_e32 v62, s0, v56
	v_mul_f32_e32 v63, s0, v57
	v_mul_f32_e32 v48, s0, v58
	v_mul_f32_e32 v49, s0, v59
	v_exp_f32_e32 v62, v62
	v_exp_f32_e32 v63, v63
	v_exp_f32_e32 v48, v48
	v_exp_f32_e32 v49, v49
	s_nop 0
	v_add_f32_e32 v62, 1.0, v62
	v_add_f32_e32 v63, 1.0, v63
	v_add_f32_e32 v48, 1.0, v48
	v_add_f32_e32 v49, 1.0, v49
	v_rcp_f32_e32 v62, v62
	v_rcp_f32_e32 v63, v63
	v_rcp_f32_e32 v48, v48
	v_rcp_f32_e32 v49, v49
	s_nop 0
	v_mul_f32_e32 v56, v56, v62
	v_mul_f32_e32 v57, v57, v63
	v_mul_f32_e32 v58, v58, v48
	v_mul_f32_e32 v59, v59, v49
	v_mul_f32_e32 v62, v20, v136
	v_mul_f32_e32 v63, v21, v136
	v_mul_f32_e32 v48, v22, v136
	v_mul_f32_e32 v49, v23, v136
	v_mul_f32_e32 v62, v62, v56
	v_mul_f32_e32 v63, v63, v57
	v_mul_f32_e32 v48, v48, v58
	v_mul_f32_e32 v49, v49, v59
	v_cvt_pk_bf16_f32 v60, v62, v63
	v_cvt_pk_bf16_f32 v61, v48, v49
	global_store_dwordx2 v134, v[60:61], s[30:31] offset:80
	s_nop 0
	v_lshlrev_b32_e32 v56, 16, v40
	v_and_b32_e32 v57, 0xffff0000, v40
	v_lshlrev_b32_e32 v58, 16, v41
	v_and_b32_e32 v59, 0xffff0000, v41
	v_mul_f32_e32 v62, s0, v56
	v_mul_f32_e32 v63, s0, v57
	v_mul_f32_e32 v48, s0, v58
	v_mul_f32_e32 v49, s0, v59
	v_exp_f32_e32 v62, v62
	v_exp_f32_e32 v63, v63
	v_exp_f32_e32 v48, v48
	v_exp_f32_e32 v49, v49
	s_nop 0
	v_add_f32_e32 v62, 1.0, v62
	v_add_f32_e32 v63, 1.0, v63
	v_add_f32_e32 v48, 1.0, v48
	v_add_f32_e32 v49, 1.0, v49
	v_rcp_f32_e32 v62, v62
	v_rcp_f32_e32 v63, v63
	v_rcp_f32_e32 v48, v48
	v_rcp_f32_e32 v49, v49
	s_nop 0
	v_mul_f32_e32 v56, v56, v62
	v_mul_f32_e32 v57, v57, v63
	v_mul_f32_e32 v58, v58, v48
	v_mul_f32_e32 v59, v59, v49
	v_mul_f32_e32 v62, v8, v136
	v_mul_f32_e32 v63, v9, v136
	v_mul_f32_e32 v48, v10, v136
	v_mul_f32_e32 v49, v11, v136
	v_mul_f32_e32 v62, v62, v56
	v_mul_f32_e32 v63, v63, v57
	v_mul_f32_e32 v48, v48, v58
	v_mul_f32_e32 v49, v49, v59
	v_cvt_pk_bf16_f32 v60, v62, v63
	v_cvt_pk_bf16_f32 v61, v48, v49
	global_store_dwordx2 v134, v[60:61], s[30:31] offset:32
	s_nop 0
	v_lshlrev_b32_e32 v56, 16, v42
	v_and_b32_e32 v57, 0xffff0000, v42
	v_lshlrev_b32_e32 v58, 16, v43
	v_and_b32_e32 v59, 0xffff0000, v43
	v_mul_f32_e32 v62, s0, v56
	v_mul_f32_e32 v63, s0, v57
	v_mul_f32_e32 v48, s0, v58
	v_mul_f32_e32 v49, s0, v59
	v_exp_f32_e32 v62, v62
	v_exp_f32_e32 v63, v63
	v_exp_f32_e32 v48, v48
	v_exp_f32_e32 v49, v49
	s_nop 0
	v_add_f32_e32 v62, 1.0, v62
	v_add_f32_e32 v63, 1.0, v63
	v_add_f32_e32 v48, 1.0, v48
	v_add_f32_e32 v49, 1.0, v49
	v_rcp_f32_e32 v62, v62
	v_rcp_f32_e32 v63, v63
	v_rcp_f32_e32 v48, v48
	v_rcp_f32_e32 v49, v49
	s_nop 0
	v_mul_f32_e32 v56, v56, v62
	v_mul_f32_e32 v57, v57, v63
	v_mul_f32_e32 v58, v58, v48
	v_mul_f32_e32 v59, v59, v49
	v_mul_f32_e32 v62, v24, v136
	v_mul_f32_e32 v63, v25, v136
	v_mul_f32_e32 v48, v26, v136
	v_mul_f32_e32 v49, v27, v136
	v_mul_f32_e32 v62, v62, v56
	v_mul_f32_e32 v63, v63, v57
	v_mul_f32_e32 v48, v48, v58
	v_mul_f32_e32 v49, v49, v59
	v_cvt_pk_bf16_f32 v60, v62, v63
	v_cvt_pk_bf16_f32 v61, v48, v49
	global_store_dwordx2 v134, v[60:61], s[30:31] offset:96
	s_nop 0
	v_lshlrev_b32_e32 v56, 16, v44
	v_and_b32_e32 v57, 0xffff0000, v44
	v_lshlrev_b32_e32 v58, 16, v45
	v_and_b32_e32 v59, 0xffff0000, v45
	v_mul_f32_e32 v62, s0, v56
	v_mul_f32_e32 v63, s0, v57
	v_mul_f32_e32 v48, s0, v58
	v_mul_f32_e32 v49, s0, v59
	v_exp_f32_e32 v62, v62
	v_exp_f32_e32 v63, v63
	v_exp_f32_e32 v48, v48
	v_exp_f32_e32 v49, v49
	s_nop 0
	v_add_f32_e32 v62, 1.0, v62
	v_add_f32_e32 v63, 1.0, v63
	v_add_f32_e32 v48, 1.0, v48
	v_add_f32_e32 v49, 1.0, v49
	v_rcp_f32_e32 v62, v62
	v_rcp_f32_e32 v63, v63
	v_rcp_f32_e32 v48, v48
	v_rcp_f32_e32 v49, v49
	s_nop 0
	v_mul_f32_e32 v56, v56, v62
	v_mul_f32_e32 v57, v57, v63
	v_mul_f32_e32 v58, v58, v48
	v_mul_f32_e32 v59, v59, v49
	v_mul_f32_e32 v62, v12, v136
	v_mul_f32_e32 v63, v13, v136
	v_mul_f32_e32 v48, v14, v136
	v_mul_f32_e32 v49, v15, v136
	v_mul_f32_e32 v62, v62, v56
	v_mul_f32_e32 v63, v63, v57
	v_mul_f32_e32 v48, v48, v58
	v_mul_f32_e32 v49, v49, v59
	v_cvt_pk_bf16_f32 v60, v62, v63
	v_cvt_pk_bf16_f32 v61, v48, v49
	global_store_dwordx2 v134, v[60:61], s[30:31] offset:48
	s_nop 0
	v_lshlrev_b32_e32 v56, 16, v46
	v_and_b32_e32 v57, 0xffff0000, v46
	v_lshlrev_b32_e32 v58, 16, v47
	v_and_b32_e32 v59, 0xffff0000, v47
	v_mul_f32_e32 v62, s0, v56
	v_mul_f32_e32 v63, s0, v57
	v_mul_f32_e32 v48, s0, v58
	v_mul_f32_e32 v49, s0, v59
	v_exp_f32_e32 v62, v62
	v_exp_f32_e32 v63, v63
	v_exp_f32_e32 v48, v48
	v_exp_f32_e32 v49, v49
	s_nop 0
	v_add_f32_e32 v62, 1.0, v62
	v_add_f32_e32 v63, 1.0, v63
	v_add_f32_e32 v48, 1.0, v48
	v_add_f32_e32 v49, 1.0, v49
	v_rcp_f32_e32 v62, v62
	v_rcp_f32_e32 v63, v63
	v_rcp_f32_e32 v48, v48
	v_rcp_f32_e32 v49, v49
	s_nop 0
	v_mul_f32_e32 v56, v56, v62
	v_mul_f32_e32 v57, v57, v63
	v_mul_f32_e32 v58, v58, v48
	v_mul_f32_e32 v59, v59, v49
	v_mul_f32_e32 v62, v28, v136
	v_mul_f32_e32 v63, v29, v136
	v_mul_f32_e32 v48, v30, v136
	v_mul_f32_e32 v49, v31, v136
	v_mul_f32_e32 v62, v62, v56
	v_mul_f32_e32 v63, v63, v57
	v_mul_f32_e32 v48, v48, v58
	v_mul_f32_e32 v49, v49, v59
	v_cvt_pk_bf16_f32 v60, v62, v63
	v_cvt_pk_bf16_f32 v61, v48, v49
	global_store_dwordx2 v134, v[60:61], s[30:31] offset:112
	s_nop 0
	s_cmp_eq_u32 s101, 1
	s_cbranch_scc1 .Lat_m_pref
	s_cmp_eq_u32 s101, 2
	s_cbranch_scc1 .Lat_g_pref
	s_branch .Lat_done
.Lat_g_pref:
	v_and_b32_e32 v32, 31, v143
	v_bfe_u32 v33, v143, 5, 1
	v_mul_u32_u24_e32 v237, 144, v32
	v_lshl_add_u32 v237, v33, 4, v237
	v_mov_b32_e32 v36, v143
	v_lshrrev_b32_e32 v37, 3, v36
	v_and_b32_e32 v38, 7, v36
	v_mul_u32_u24_e32 v37, 144, v37
	v_lshl_add_u32 v179, v38, 4, v37
	v_add_u32_e32 v36, 512, v143
	v_lshrrev_b32_e32 v37, 3, v36
	v_and_b32_e32 v38, 7, v36
	v_mul_u32_u24_e32 v37, 144, v37
	v_lshl_add_u32 v181, v38, 4, v37
	v_mov_b32_e32 v130, 0
	v_mov_b32_e32 v131, 0
	v_mov_b32_e32 v0, 0
	v_mov_b32_e32 v1, 0
	v_mov_b32_e32 v2, 0
	v_mov_b32_e32 v3, 0
	v_mov_b32_e32 v4, 0
	v_mov_b32_e32 v5, 0
	v_mov_b32_e32 v6, 0
	v_mov_b32_e32 v7, 0
	v_mov_b32_e32 v8, 0
	v_mov_b32_e32 v9, 0
	v_mov_b32_e32 v10, 0
	v_mov_b32_e32 v11, 0
	v_mov_b32_e32 v12, 0
	v_mov_b32_e32 v13, 0
	v_mov_b32_e32 v14, 0
	v_mov_b32_e32 v15, 0
	v_mov_b32_e32 v16, 0
	v_mov_b32_e32 v17, 0
	v_mov_b32_e32 v18, 0
	v_mov_b32_e32 v19, 0
	v_mov_b32_e32 v20, 0
	v_mov_b32_e32 v21, 0
	v_mov_b32_e32 v22, 0
	v_mov_b32_e32 v23, 0
	v_mov_b32_e32 v24, 0
	v_mov_b32_e32 v25, 0
	v_mov_b32_e32 v26, 0
	v_mov_b32_e32 v27, 0
	v_mov_b32_e32 v28, 0
	v_mov_b32_e32 v29, 0
	v_mov_b32_e32 v30, 0
	v_mov_b32_e32 v31, 0
	s_waitcnt vmcnt(10)
	v_add_u32_e32 v128, s64, v179
	ds_write_b128 v128, v[208:211]
	v_add_u32_e32 v128, s64, v181
	ds_write_b128 v128, v[212:215]
	v_add_u32_e32 v128, s70, v183
	ds_write_b128 v128, v[220:223]
	ds_write_b128 v128, v[224:227] offset:8192
	global_load_dwordx4 v[208:211], v232, s[16:17]
	global_load_dwordx4 v[212:215], v239, s[16:17]
	global_load_dwordx4 v[220:223], v232, s[22:23]
	global_load_dwordx4 v[224:227], v239, s[22:23]
	s_add_u32 s16, s16, 16384
	s_addc_u32 s17, s17, 0
	s_add_u32 s22, s22, 16384
	s_addc_u32 s23, s23, 0
	s_waitcnt vmcnt(12)
	v_add_u32_e32 v128, s65, v179
	ds_write_b128 v128, v[144:147]
	v_add_u32_e32 v128, s65, v181
	ds_write_b128 v128, v[148:151]
	v_add_u32_e32 v140, s64, v237
	s_waitcnt lgkmcnt(0)
	s_barrier
	s_branch .Lat_g_body
.Lat_g_first:
	v_and_b32_e32 v32, 31, v143
	v_bfe_u32 v33, v143, 5, 1
	v_mul_u32_u24_e32 v237, 144, v32
	v_lshl_add_u32 v237, v33, 4, v237
	v_mov_b32_e32 v36, v143
	v_lshrrev_b32_e32 v37, 3, v36
	v_and_b32_e32 v38, 7, v36
	v_mul_u32_u24_e32 v37, 144, v37
	v_lshl_add_u32 v179, v38, 4, v37
	v_add_u32_e32 v36, 512, v143
	v_lshrrev_b32_e32 v37, 3, v36
	v_and_b32_e32 v38, 7, v36
	v_mul_u32_u24_e32 v37, 144, v37
	v_lshl_add_u32 v181, v38, 4, v37
	v_mov_b32_e32 v130, 0
	v_mov_b32_e32 v131, 0
	v_mov_b32_e32 v0, 0
	v_mov_b32_e32 v1, 0
	v_mov_b32_e32 v2, 0
	v_mov_b32_e32 v3, 0
	v_mov_b32_e32 v4, 0
	v_mov_b32_e32 v5, 0
	v_mov_b32_e32 v6, 0
	v_mov_b32_e32 v7, 0
	v_mov_b32_e32 v8, 0
	v_mov_b32_e32 v9, 0
	v_mov_b32_e32 v10, 0
	v_mov_b32_e32 v11, 0
	v_mov_b32_e32 v12, 0
	v_mov_b32_e32 v13, 0
	v_mov_b32_e32 v14, 0
	v_mov_b32_e32 v15, 0
	v_mov_b32_e32 v16, 0
	v_mov_b32_e32 v17, 0
	v_mov_b32_e32 v18, 0
	v_mov_b32_e32 v19, 0
	v_mov_b32_e32 v20, 0
	v_mov_b32_e32 v21, 0
	v_mov_b32_e32 v22, 0
	v_mov_b32_e32 v23, 0
	v_mov_b32_e32 v24, 0
	v_mov_b32_e32 v25, 0
	v_mov_b32_e32 v26, 0
	v_mov_b32_e32 v27, 0
	v_mov_b32_e32 v28, 0
	v_mov_b32_e32 v29, 0
	v_mov_b32_e32 v30, 0
	v_mov_b32_e32 v31, 0
	s_waitcnt vmcnt(2)
	v_add_u32_e32 v128, s64, v179
	ds_write_b128 v128, v[208:211]
	v_add_u32_e32 v128, s64, v181
	ds_write_b128 v128, v[212:215]
	v_add_u32_e32 v128, s70, v183
	ds_write_b128 v128, v[220:223]
	ds_write_b128 v128, v[224:227] offset:8192
	global_load_dwordx4 v[208:211], v232, s[16:17]
	global_load_dwordx4 v[212:215], v239, s[16:17]
	global_load_dwordx4 v[220:223], v232, s[22:23]
	global_load_dwordx4 v[224:227], v239, s[22:23]
	s_add_u32 s16, s16, 16384
	s_addc_u32 s17, s17, 0
	s_add_u32 s22, s22, 16384
	s_addc_u32 s23, s23, 0
	s_waitcnt vmcnt(4)
	v_add_u32_e32 v128, s65, v179
	ds_write_b128 v128, v[144:147]
	v_add_u32_e32 v128, s65, v181
	ds_write_b128 v128, v[148:151]
	v_add_u32_e32 v140, s64, v237
	s_waitcnt lgkmcnt(0)
	s_barrier
.Lat_g_body:
	ds_read_b128 v[144:147], v140 offset:0
	ds_read_b128 v[148:151], v140 offset:32
	ds_read_b128 v[152:155], v140 offset:64
	ds_read_b128 v[156:159], v140 offset:96
	ds_read_b128 v[160:163], v140 offset:4608
	ds_read_b128 v[164:167], v140 offset:4640
	s_waitcnt lgkmcnt(5)
	v_mfma_f32_32x32x16_bf16 v[32:47], v[144:147], v[184:187], 0
	ds_read_b128 v[168:171], v140 offset:4672
	s_waitcnt lgkmcnt(5)
	v_mfma_f32_32x32x16_bf16 v[32:47], v[148:151], v[188:191], v[32:47]
	ds_read_b128 v[172:175], v140 offset:4704
	s_waitcnt lgkmcnt(5)
	v_mfma_f32_32x32x16_bf16 v[32:47], v[152:155], v[192:195], v[32:47]
	s_waitcnt lgkmcnt(4)
	v_mfma_f32_32x32x16_bf16 v[32:47], v[156:159], v[196:199], v[32:47]
	s_waitcnt lgkmcnt(3)
	v_mfma_f32_32x32x16_bf16 v[48:63], v[160:163], v[184:187], 0
	s_waitcnt lgkmcnt(2)
	v_mfma_f32_32x32x16_bf16 v[48:63], v[164:167], v[188:191], v[48:63]
	s_waitcnt lgkmcnt(1)
	v_mfma_f32_32x32x16_bf16 v[48:63], v[168:171], v[192:195], v[48:63]
	s_waitcnt lgkmcnt(0)
	v_mfma_f32_32x32x16_bf16 v[48:63], v[172:175], v[196:199], v[48:63]
	s_nop 7
	s_nop 3
	v_add_u32_e32 v140, s64, v237
	v_add_u32_e32 v141, s65, v237
	v_add_u32_e32 v176, s69, v238
	v_add_u32_e32 v177, s70, v238
	ds_read_b128 v[144:147], v140 offset:9216
	ds_read_b128 v[148:151], v140 offset:9248
	ds_read_b128 v[152:155], v140 offset:9280
	ds_read_b128 v[156:159], v140 offset:9312
	ds_read_b128 v[160:163], v140 offset:13824
	ds_read_b128 v[164:167], v140 offset:13856
	s_waitcnt lgkmcnt(5)
	v_mfma_f32_32x32x16_bf16 v[64:79], v[144:147], v[184:187], 0
	ds_read_b128 v[168:171], v140 offset:13888
	v_exp_f32_e32 v32, v32
	v_exp_f32_e32 v33, v33
	v_add_f32_e32 v130, v130, v32
	v_add_f32_e32 v131, v131, v33
	v_cvt_pk_bf16_f32 v96, v32, v33
	v_exp_f32_e32 v34, v34
	v_exp_f32_e32 v35, v35
	v_add_f32_e32 v130, v130, v34
	v_add_f32_e32 v131, v131, v35
	v_cvt_pk_bf16_f32 v97, v34, v35
	s_waitcnt vmcnt(3)
	v_add_u32_e32 v128, s68, v179
	ds_write_b128 v128, v[208:211]
	global_load_dwordx4 v[208:211], v232, s[16:17]
	s_waitcnt lgkmcnt(6)
	v_mfma_f32_32x32x16_bf16 v[64:79], v[148:151], v[188:191], v[64:79]
	ds_read_b128 v[172:175], v140 offset:13920
	v_exp_f32_e32 v36, v36
	v_exp_f32_e32 v37, v37
	v_add_f32_e32 v130, v130, v36
	v_add_f32_e32 v131, v131, v37
	v_cvt_pk_bf16_f32 v98, v36, v37
	v_exp_f32_e32 v38, v38
	v_exp_f32_e32 v39, v39
	v_add_f32_e32 v130, v130, v38
	v_add_f32_e32 v131, v131, v39
	v_cvt_pk_bf16_f32 v99, v38, v39
	s_waitcnt vmcnt(3)
	v_add_u32_e32 v128, s68, v181
	ds_write_b128 v128, v[212:215]
	global_load_dwordx4 v[212:215], v239, s[16:17]
	s_waitcnt lgkmcnt(7)
	v_mfma_f32_32x32x16_bf16 v[64:79], v[152:155], v[192:195], v[64:79]
	ds_read_b128 v[144:147], v141 offset:0
	v_exp_f32_e32 v40, v40
	v_exp_f32_e32 v41, v41
	v_add_f32_e32 v130, v130, v40
	v_add_f32_e32 v131, v131, v41
	v_cvt_pk_bf16_f32 v100, v40, v41
	v_exp_f32_e32 v42, v42
	v_exp_f32_e32 v43, v43
	v_add_f32_e32 v130, v130, v42
	v_add_f32_e32 v131, v131, v43
	v_cvt_pk_bf16_f32 v101, v42, v43
	s_waitcnt vmcnt(3)
	v_add_u32_e32 v128, s71, v183
	ds_write_b128 v128, v[220:223]
	global_load_dwordx4 v[220:223], v232, s[22:23]
	s_waitcnt lgkmcnt(8)
	v_mfma_f32_32x32x16_bf16 v[64:79], v[156:159], v[196:199], v[64:79]
	ds_read_b128 v[148:151], v141 offset:32
	v_exp_f32_e32 v44, v44
	v_exp_f32_e32 v45, v45
	v_add_f32_e32 v130, v130, v44
	v_add_f32_e32 v131, v131, v45
	v_cvt_pk_bf16_f32 v102, v44, v45
	v_exp_f32_e32 v46, v46
	v_exp_f32_e32 v47, v47
	v_add_f32_e32 v130, v130, v46
	v_add_f32_e32 v131, v131, v47
	v_cvt_pk_bf16_f32 v103, v46, v47
	s_waitcnt vmcnt(3)
	v_add_u32_e32 v128, s71, v183
	ds_write_b128 v128, v[224:227] offset:8192
	global_load_dwordx4 v[224:227], v239, s[22:23]
	s_waitcnt lgkmcnt(9)
	v_mfma_f32_32x32x16_bf16 v[80:95], v[160:163], v[184:187], 0
	ds_read_b128 v[152:155], v141 offset:64
	v_exp_f32_e32 v48, v48
	v_exp_f32_e32 v49, v49
	v_add_f32_e32 v130, v130, v48
	v_add_f32_e32 v131, v131, v49
	v_cvt_pk_bf16_f32 v104, v48, v49
	v_exp_f32_e32 v50, v50
	v_exp_f32_e32 v51, v51
	v_add_f32_e32 v130, v130, v50
	v_add_f32_e32 v131, v131, v51
	v_cvt_pk_bf16_f32 v105, v50, v51
	s_waitcnt lgkmcnt(9)
	v_mfma_f32_32x32x16_bf16 v[80:95], v[164:167], v[188:191], v[80:95]
	ds_read_b128 v[156:159], v141 offset:96
	v_exp_f32_e32 v52, v52
	v_exp_f32_e32 v53, v53
	v_add_f32_e32 v130, v130, v52
	v_add_f32_e32 v131, v131, v53
	v_cvt_pk_bf16_f32 v106, v52, v53
	v_exp_f32_e32 v54, v54
	v_exp_f32_e32 v55, v55
	v_add_f32_e32 v130, v130, v54
	v_add_f32_e32 v131, v131, v55
	v_cvt_pk_bf16_f32 v107, v54, v55
	s_waitcnt lgkmcnt(9)
	v_mfma_f32_32x32x16_bf16 v[80:95], v[168:171], v[192:195], v[80:95]
	ds_read_b128 v[160:163], v141 offset:4608
	v_exp_f32_e32 v56, v56
	v_exp_f32_e32 v57, v57
	v_add_f32_e32 v130, v130, v56
	v_add_f32_e32 v131, v131, v57
	v_cvt_pk_bf16_f32 v108, v56, v57
	v_exp_f32_e32 v58, v58
	v_exp_f32_e32 v59, v59
	v_add_f32_e32 v130, v130, v58
	v_add_f32_e32 v131, v131, v59
	v_cvt_pk_bf16_f32 v109, v58, v59
	s_waitcnt lgkmcnt(8)
	v_mfma_f32_32x32x16_bf16 v[80:95], v[172:175], v[196:199], v[80:95]
	ds_read_b128 v[164:167], v141 offset:4640
	v_exp_f32_e32 v60, v60
	v_exp_f32_e32 v61, v61
	v_add_f32_e32 v130, v130, v60
	v_add_f32_e32 v131, v131, v61
	v_cvt_pk_bf16_f32 v110, v60, v61
	v_exp_f32_e32 v62, v62
	v_exp_f32_e32 v63, v63
	v_add_f32_e32 v130, v130, v62
	v_add_f32_e32 v131, v131, v63
	v_cvt_pk_bf16_f32 v111, v62, v63
	s_add_u32 s16, s16, 16384
	s_addc_u32 s17, s17, 0
	s_add_u32 s22, s22, 16384
	s_addc_u32 s23, s23, 0
	s_waitcnt lgkmcnt(7)
	v_mfma_f32_32x32x16_bf16 v[32:47], v[144:147], v[184:187], 0
	ds_read_b128 v[168:171], v141 offset:4672
	v_exp_f32_e32 v64, v64
	v_exp_f32_e32 v65, v65
	v_add_f32_e32 v130, v130, v64
	v_add_f32_e32 v131, v131, v65
	v_cvt_pk_bf16_f32 v112, v64, v65
	s_waitcnt lgkmcnt(6)
	v_mfma_f32_32x32x16_bf16 v[32:47], v[148:151], v[188:191], v[32:47]
	ds_read_b128 v[172:175], v141 offset:4704
	v_exp_f32_e32 v66, v66
	v_exp_f32_e32 v67, v67
	v_add_f32_e32 v130, v130, v66
	v_add_f32_e32 v131, v131, v67
	v_cvt_pk_bf16_f32 v113, v66, v67
	s_waitcnt lgkmcnt(5)
	v_mfma_f32_32x32x16_bf16 v[32:47], v[152:155], v[192:195], v[32:47]
	ds_read_b64_tr_b16 v[144:145], v177 offset:0
	ds_read_b64_tr_b16 v[146:147], v177 offset:1024
	v_exp_f32_e32 v68, v68
	v_exp_f32_e32 v69, v69
	v_add_f32_e32 v130, v130, v68
	v_add_f32_e32 v131, v131, v69
	v_cvt_pk_bf16_f32 v114, v68, v69
	s_waitcnt lgkmcnt(6)
	v_mfma_f32_32x32x16_bf16 v[32:47], v[156:159], v[196:199], v[32:47]
	ds_read_b64_tr_b16 v[148:149], v177 offset:512
	ds_read_b64_tr_b16 v[150:151], v177 offset:1536
	v_exp_f32_e32 v70, v70
	v_exp_f32_e32 v71, v71
	v_add_f32_e32 v130, v130, v70
	v_add_f32_e32 v131, v131, v71
	v_cvt_pk_bf16_f32 v115, v70, v71
	s_waitcnt lgkmcnt(7)
	v_mfma_f32_32x32x16_bf16 v[48:63], v[160:163], v[184:187], 0
	ds_read_b64_tr_b16 v[152:153], v177 offset:2048
	ds_read_b64_tr_b16 v[154:155], v177 offset:3072
	v_exp_f32_e32 v72, v72
	v_exp_f32_e32 v73, v73
	v_add_f32_e32 v130, v130, v72
	v_add_f32_e32 v131, v131, v73
	v_cvt_pk_bf16_f32 v116, v72, v73
	s_waitcnt lgkmcnt(8)
	v_mfma_f32_32x32x16_bf16 v[48:63], v[164:167], v[188:191], v[48:63]
	ds_read_b64_tr_b16 v[156:157], v177 offset:2560
	ds_read_b64_tr_b16 v[158:159], v177 offset:3584
	v_exp_f32_e32 v74, v74
	v_exp_f32_e32 v75, v75
	v_add_f32_e32 v130, v130, v74
	v_add_f32_e32 v131, v131, v75
	v_cvt_pk_bf16_f32 v117, v74, v75
	s_waitcnt lgkmcnt(9)
	v_mfma_f32_32x32x16_bf16 v[48:63], v[168:171], v[192:195], v[48:63]
	ds_read_b64_tr_b16 v[160:161], v177 offset:4096
	ds_read_b64_tr_b16 v[162:163], v177 offset:5120
	v_exp_f32_e32 v76, v76
	v_exp_f32_e32 v77, v77
	v_add_f32_e32 v130, v130, v76
	v_add_f32_e32 v131, v131, v77
	v_cvt_pk_bf16_f32 v118, v76, v77
	s_waitcnt lgkmcnt(10)
	v_mfma_f32_32x32x16_bf16 v[48:63], v[172:175], v[196:199], v[48:63]
	ds_read_b64_tr_b16 v[164:165], v177 offset:4608
	ds_read_b64_tr_b16 v[166:167], v177 offset:5632
	v_exp_f32_e32 v78, v78
	v_exp_f32_e32 v79, v79
	v_add_f32_e32 v130, v130, v78
	v_add_f32_e32 v131, v131, v79
	v_cvt_pk_bf16_f32 v119, v78, v79
	s_waitcnt lgkmcnt(10)
	v_mfma_f32_32x32x16_bf16 v[0:15], v[144:147], v[96:99], v[0:15]
	ds_read_b64_tr_b16 v[168:169], v177 offset:6144
	ds_read_b64_tr_b16 v[170:171], v177 offset:7168
	v_exp_f32_e32 v80, v80
	v_exp_f32_e32 v81, v81
	v_add_f32_e32 v130, v130, v80
	v_add_f32_e32 v131, v131, v81
	v_cvt_pk_bf16_f32 v120, v80, v81
	s_waitcnt lgkmcnt(10)
	v_mfma_f32_32x32x16_bf16 v[16:31], v[148:151], v[96:99], v[16:31]
	ds_read_b64_tr_b16 v[172:173], v177 offset:6656
	ds_read_b64_tr_b16 v[174:175], v177 offset:7680
	v_exp_f32_e32 v82, v82
	v_exp_f32_e32 v83, v83
	v_add_f32_e32 v130, v130, v82
	v_add_f32_e32 v131, v131, v83
	v_cvt_pk_bf16_f32 v121, v82, v83
	s_waitcnt lgkmcnt(10)
	v_mfma_f32_32x32x16_bf16 v[0:15], v[152:155], v[100:103], v[0:15]
	ds_read_b128 v[144:147], v141 offset:9216
	v_exp_f32_e32 v84, v84
	v_exp_f32_e32 v85, v85
	v_add_f32_e32 v130, v130, v84
	v_add_f32_e32 v131, v131, v85
	v_cvt_pk_bf16_f32 v122, v84, v85
	s_waitcnt lgkmcnt(9)
	v_mfma_f32_32x32x16_bf16 v[16:31], v[156:159], v[100:103], v[16:31]
	ds_read_b128 v[148:151], v141 offset:9248
	v_exp_f32_e32 v86, v86
	v_exp_f32_e32 v87, v87
	v_add_f32_e32 v130, v130, v86
	v_add_f32_e32 v131, v131, v87
	v_cvt_pk_bf16_f32 v123, v86, v87
	s_waitcnt lgkmcnt(8)
	v_mfma_f32_32x32x16_bf16 v[0:15], v[160:163], v[104:107], v[0:15]
	ds_read_b128 v[152:155], v141 offset:9280
	v_exp_f32_e32 v88, v88
	v_exp_f32_e32 v89, v89
	v_add_f32_e32 v130, v130, v88
	v_add_f32_e32 v131, v131, v89
	v_cvt_pk_bf16_f32 v124, v88, v89
	s_waitcnt lgkmcnt(7)
	v_mfma_f32_32x32x16_bf16 v[16:31], v[164:167], v[104:107], v[16:31]
	ds_read_b128 v[156:159], v141 offset:9312
	v_exp_f32_e32 v90, v90
	v_exp_f32_e32 v91, v91
	v_add_f32_e32 v130, v130, v90
	v_add_f32_e32 v131, v131, v91
	v_cvt_pk_bf16_f32 v125, v90, v91
	s_waitcnt lgkmcnt(6)
	v_mfma_f32_32x32x16_bf16 v[0:15], v[168:171], v[108:111], v[0:15]
	ds_read_b128 v[160:163], v141 offset:13824
	v_exp_f32_e32 v92, v92
	v_exp_f32_e32 v93, v93
	v_add_f32_e32 v130, v130, v92
	v_add_f32_e32 v131, v131, v93
	v_cvt_pk_bf16_f32 v126, v92, v93
	s_waitcnt lgkmcnt(5)
	v_mfma_f32_32x32x16_bf16 v[16:31], v[172:175], v[108:111], v[16:31]
	ds_read_b128 v[164:167], v141 offset:13856
	v_exp_f32_e32 v94, v94
	v_exp_f32_e32 v95, v95
	v_add_f32_e32 v130, v130, v94
	v_add_f32_e32 v131, v131, v95
	v_cvt_pk_bf16_f32 v127, v94, v95
	s_mov_b32 s0, s64
	s_mov_b32 s64, s65
	s_mov_b32 s65, s68
	s_mov_b32 s68, s0
	s_mov_b32 s0, s69
	s_mov_b32 s69, s70
	s_mov_b32 s70, s71
	s_mov_b32 s71, s0
	s_barrier
	s_cmp_eq_u32 s27, 0
	s_cbranch_scc1 .Lat_g_last

.Lat_g_last:
	v_add_u32_e32 v140, s64, v237
	v_add_u32_e32 v141, s65, v237
	v_add_u32_e32 v176, s69, v238
	v_add_u32_e32 v177, s70, v238
	s_waitcnt lgkmcnt(5)
	v_mfma_f32_32x32x16_bf16 v[64:79], v[144:147], v[184:187], 0
	ds_read_b128 v[168:171], v140 offset:13888
	v_exp_f32_e32 v32, v32
	v_exp_f32_e32 v33, v33
	v_add_f32_e32 v130, v130, v32
	v_add_f32_e32 v131, v131, v33
	v_cvt_pk_bf16_f32 v96, v32, v33
	s_waitcnt lgkmcnt(5)
	v_mfma_f32_32x32x16_bf16 v[64:79], v[148:151], v[188:191], v[64:79]
	ds_read_b128 v[172:175], v140 offset:13920
	v_exp_f32_e32 v34, v34
	v_exp_f32_e32 v35, v35
	v_add_f32_e32 v130, v130, v34
	v_add_f32_e32 v131, v131, v35
	v_cvt_pk_bf16_f32 v97, v34, v35
	s_waitcnt lgkmcnt(5)
	v_mfma_f32_32x32x16_bf16 v[64:79], v[152:155], v[192:195], v[64:79]
	ds_read_b64_tr_b16 v[144:145], v176 offset:8192
	ds_read_b64_tr_b16 v[146:147], v176 offset:9216
	v_exp_f32_e32 v36, v36
	v_exp_f32_e32 v37, v37
	v_add_f32_e32 v130, v130, v36
	v_add_f32_e32 v131, v131, v37
	v_cvt_pk_bf16_f32 v98, v36, v37
	s_waitcnt lgkmcnt(6)
	v_mfma_f32_32x32x16_bf16 v[64:79], v[156:159], v[196:199], v[64:79]
	ds_read_b64_tr_b16 v[148:149], v176 offset:8704
	ds_read_b64_tr_b16 v[150:151], v176 offset:9728
	v_exp_f32_e32 v38, v38
	v_exp_f32_e32 v39, v39
	v_add_f32_e32 v130, v130, v38
	v_add_f32_e32 v131, v131, v39
	v_cvt_pk_bf16_f32 v99, v38, v39
	s_waitcnt lgkmcnt(7)
	v_mfma_f32_32x32x16_bf16 v[80:95], v[160:163], v[184:187], 0
	ds_read_b64_tr_b16 v[152:153], v176 offset:10240
	ds_read_b64_tr_b16 v[154:155], v176 offset:11264
	v_exp_f32_e32 v40, v40
	v_exp_f32_e32 v41, v41
	v_add_f32_e32 v130, v130, v40
	v_add_f32_e32 v131, v131, v41
	v_cvt_pk_bf16_f32 v100, v40, v41
	s_waitcnt lgkmcnt(8)
	v_mfma_f32_32x32x16_bf16 v[80:95], v[164:167], v[188:191], v[80:95]
	ds_read_b64_tr_b16 v[156:157], v176 offset:10752
	ds_read_b64_tr_b16 v[158:159], v176 offset:11776
	v_exp_f32_e32 v42, v42
	v_exp_f32_e32 v43, v43
	v_add_f32_e32 v130, v130, v42
	v_add_f32_e32 v131, v131, v43
	v_cvt_pk_bf16_f32 v101, v42, v43
	s_waitcnt lgkmcnt(9)
	v_mfma_f32_32x32x16_bf16 v[80:95], v[168:171], v[192:195], v[80:95]
	ds_read_b64_tr_b16 v[160:161], v176 offset:12288
	ds_read_b64_tr_b16 v[162:163], v176 offset:13312
	v_exp_f32_e32 v44, v44
	v_exp_f32_e32 v45, v45
	v_add_f32_e32 v130, v130, v44
	v_add_f32_e32 v131, v131, v45
	v_cvt_pk_bf16_f32 v102, v44, v45
	s_waitcnt lgkmcnt(10)
	v_mfma_f32_32x32x16_bf16 v[80:95], v[172:175], v[196:199], v[80:95]
	ds_read_b64_tr_b16 v[164:165], v176 offset:12800
	ds_read_b64_tr_b16 v[166:167], v176 offset:13824
	v_exp_f32_e32 v46, v46
	v_exp_f32_e32 v47, v47
	v_add_f32_e32 v130, v130, v46
	v_add_f32_e32 v131, v131, v47
	v_cvt_pk_bf16_f32 v103, v46, v47
	s_waitcnt lgkmcnt(10)
	v_mfma_f32_32x32x16_bf16 v[0:15], v[144:147], v[112:115], v[0:15]
	ds_read_b64_tr_b16 v[168:169], v176 offset:14336
	ds_read_b64_tr_b16 v[170:171], v176 offset:15360
	v_exp_f32_e32 v48, v48
	v_exp_f32_e32 v49, v49
	v_add_f32_e32 v130, v130, v48
	v_add_f32_e32 v131, v131, v49
	v_cvt_pk_bf16_f32 v104, v48, v49
	s_waitcnt lgkmcnt(10)
	v_mfma_f32_32x32x16_bf16 v[16:31], v[148:151], v[112:115], v[16:31]
	ds_read_b64_tr_b16 v[172:173], v176 offset:14848
	ds_read_b64_tr_b16 v[174:175], v176 offset:15872
	v_exp_f32_e32 v50, v50
	v_exp_f32_e32 v51, v51
	v_add_f32_e32 v130, v130, v50
	v_add_f32_e32 v131, v131, v51
	v_cvt_pk_bf16_f32 v105, v50, v51
	s_waitcnt lgkmcnt(10)
	v_mfma_f32_32x32x16_bf16 v[0:15], v[152:155], v[116:119], v[0:15]
	ds_read_b64_tr_b16 v[144:145], v177 offset:0
	ds_read_b64_tr_b16 v[146:147], v177 offset:1024
	v_exp_f32_e32 v52, v52
	v_exp_f32_e32 v53, v53
	v_add_f32_e32 v130, v130, v52
	v_add_f32_e32 v131, v131, v53
	v_cvt_pk_bf16_f32 v106, v52, v53
	s_waitcnt lgkmcnt(10)
	v_mfma_f32_32x32x16_bf16 v[16:31], v[156:159], v[116:119], v[16:31]
	ds_read_b64_tr_b16 v[148:149], v177 offset:512
	ds_read_b64_tr_b16 v[150:151], v177 offset:1536
	v_exp_f32_e32 v54, v54
	v_exp_f32_e32 v55, v55
	v_add_f32_e32 v130, v130, v54
	v_add_f32_e32 v131, v131, v55
	v_cvt_pk_bf16_f32 v107, v54, v55
	s_waitcnt lgkmcnt(10)
	v_mfma_f32_32x32x16_bf16 v[0:15], v[160:163], v[120:123], v[0:15]
	ds_read_b64_tr_b16 v[152:153], v177 offset:2048
	ds_read_b64_tr_b16 v[154:155], v177 offset:3072
	v_exp_f32_e32 v56, v56
	v_exp_f32_e32 v57, v57
	v_add_f32_e32 v130, v130, v56
	v_add_f32_e32 v131, v131, v57
	v_cvt_pk_bf16_f32 v108, v56, v57
	s_waitcnt lgkmcnt(10)
	v_mfma_f32_32x32x16_bf16 v[16:31], v[164:167], v[120:123], v[16:31]
	ds_read_b64_tr_b16 v[156:157], v177 offset:2560
	ds_read_b64_tr_b16 v[158:159], v177 offset:3584
	v_exp_f32_e32 v58, v58
	v_exp_f32_e32 v59, v59
	v_add_f32_e32 v130, v130, v58
	v_add_f32_e32 v131, v131, v59
	v_cvt_pk_bf16_f32 v109, v58, v59
	s_waitcnt lgkmcnt(10)
	v_mfma_f32_32x32x16_bf16 v[0:15], v[168:171], v[124:127], v[0:15]
	ds_read_b64_tr_b16 v[160:161], v177 offset:4096
	ds_read_b64_tr_b16 v[162:163], v177 offset:5120
	v_exp_f32_e32 v60, v60
	v_exp_f32_e32 v61, v61
	v_add_f32_e32 v130, v130, v60
	v_add_f32_e32 v131, v131, v61
	v_cvt_pk_bf16_f32 v110, v60, v61
	s_waitcnt lgkmcnt(10)
	v_mfma_f32_32x32x16_bf16 v[16:31], v[172:175], v[124:127], v[16:31]
	ds_read_b64_tr_b16 v[164:165], v177 offset:4608
	ds_read_b64_tr_b16 v[166:167], v177 offset:5632
	v_exp_f32_e32 v62, v62
	v_exp_f32_e32 v63, v63
	v_add_f32_e32 v130, v130, v62
	v_add_f32_e32 v131, v131, v63
	v_cvt_pk_bf16_f32 v111, v62, v63
	s_waitcnt lgkmcnt(10)
	v_mfma_f32_32x32x16_bf16 v[0:15], v[144:147], v[96:99], v[0:15]
	ds_read_b64_tr_b16 v[168:169], v177 offset:6144
	ds_read_b64_tr_b16 v[170:171], v177 offset:7168
	v_exp_f32_e32 v64, v64
	v_exp_f32_e32 v65, v65
	v_add_f32_e32 v130, v130, v64
	v_add_f32_e32 v131, v131, v65
	v_cvt_pk_bf16_f32 v112, v64, v65
	v_exp_f32_e32 v66, v66
	v_exp_f32_e32 v67, v67
	v_add_f32_e32 v130, v130, v66
	v_add_f32_e32 v131, v131, v67
	v_cvt_pk_bf16_f32 v113, v66, v67
	global_load_dwordx2 v[32:33], v133, s[12:13] offset:0
	s_waitcnt lgkmcnt(10)
	v_mfma_f32_32x32x16_bf16 v[16:31], v[148:151], v[96:99], v[16:31]
	ds_read_b64_tr_b16 v[172:173], v177 offset:6656
	ds_read_b64_tr_b16 v[174:175], v177 offset:7680
	v_exp_f32_e32 v68, v68
	v_exp_f32_e32 v69, v69
	v_add_f32_e32 v130, v130, v68
	v_add_f32_e32 v131, v131, v69
	v_cvt_pk_bf16_f32 v114, v68, v69
	v_exp_f32_e32 v70, v70
	v_exp_f32_e32 v71, v71
	v_add_f32_e32 v130, v130, v70
	v_add_f32_e32 v131, v131, v71
	v_cvt_pk_bf16_f32 v115, v70, v71
	global_load_dwordx2 v[34:35], v133, s[12:13] offset:64
	s_waitcnt lgkmcnt(10)
	v_mfma_f32_32x32x16_bf16 v[0:15], v[152:155], v[100:103], v[0:15]
	v_exp_f32_e32 v72, v72
	v_exp_f32_e32 v73, v73
	v_add_f32_e32 v130, v130, v72
	v_add_f32_e32 v131, v131, v73
	v_cvt_pk_bf16_f32 v116, v72, v73
	v_exp_f32_e32 v74, v74
	v_exp_f32_e32 v75, v75
	v_add_f32_e32 v130, v130, v74
	v_add_f32_e32 v131, v131, v75
	v_cvt_pk_bf16_f32 v117, v74, v75
	global_load_dwordx2 v[36:37], v133, s[12:13] offset:16
	s_waitcnt lgkmcnt(8)
	v_mfma_f32_32x32x16_bf16 v[16:31], v[156:159], v[100:103], v[16:31]
	v_exp_f32_e32 v76, v76
	v_exp_f32_e32 v77, v77
	v_add_f32_e32 v130, v130, v76
	v_add_f32_e32 v131, v131, v77
	v_cvt_pk_bf16_f32 v118, v76, v77
	v_exp_f32_e32 v78, v78
	v_exp_f32_e32 v79, v79
	v_add_f32_e32 v130, v130, v78
	v_add_f32_e32 v131, v131, v79
	v_cvt_pk_bf16_f32 v119, v78, v79
	global_load_dwordx2 v[38:39], v133, s[12:13] offset:80
	s_waitcnt lgkmcnt(6)
	v_mfma_f32_32x32x16_bf16 v[0:15], v[160:163], v[104:107], v[0:15]
	v_exp_f32_e32 v80, v80
	v_exp_f32_e32 v81, v81
	v_add_f32_e32 v130, v130, v80
	v_add_f32_e32 v131, v131, v81
	v_cvt_pk_bf16_f32 v120, v80, v81
	v_exp_f32_e32 v82, v82
	v_exp_f32_e32 v83, v83
	v_add_f32_e32 v130, v130, v82
	v_add_f32_e32 v131, v131, v83
	v_cvt_pk_bf16_f32 v121, v82, v83
	global_load_dwordx2 v[40:41], v133, s[12:13] offset:32
	s_waitcnt lgkmcnt(4)
	v_mfma_f32_32x32x16_bf16 v[16:31], v[164:167], v[104:107], v[16:31]
	v_exp_f32_e32 v84, v84
	v_exp_f32_e32 v85, v85
	v_add_f32_e32 v130, v130, v84
	v_add_f32_e32 v131, v131, v85
	v_cvt_pk_bf16_f32 v122, v84, v85
	v_exp_f32_e32 v86, v86
	v_exp_f32_e32 v87, v87
	v_add_f32_e32 v130, v130, v86
	v_add_f32_e32 v131, v131, v87
	v_cvt_pk_bf16_f32 v123, v86, v87
	global_load_dwordx2 v[42:43], v133, s[12:13] offset:96
	s_waitcnt lgkmcnt(2)
	v_mfma_f32_32x32x16_bf16 v[0:15], v[168:171], v[108:111], v[0:15]
	v_exp_f32_e32 v88, v88
	v_exp_f32_e32 v89, v89
	v_add_f32_e32 v130, v130, v88
	v_add_f32_e32 v131, v131, v89
	v_cvt_pk_bf16_f32 v124, v88, v89
	v_exp_f32_e32 v90, v90
	v_exp_f32_e32 v91, v91
	v_add_f32_e32 v130, v130, v90
	v_add_f32_e32 v131, v131, v91
	v_cvt_pk_bf16_f32 v125, v90, v91
	global_load_dwordx2 v[44:45], v133, s[12:13] offset:48
	s_waitcnt lgkmcnt(0)
	v_mfma_f32_32x32x16_bf16 v[16:31], v[172:175], v[108:111], v[16:31]
	v_exp_f32_e32 v92, v92
	v_exp_f32_e32 v93, v93
	v_add_f32_e32 v130, v130, v92
	v_add_f32_e32 v131, v131, v93
	v_cvt_pk_bf16_f32 v126, v92, v93
	v_exp_f32_e32 v94, v94
	v_exp_f32_e32 v95, v95
	v_add_f32_e32 v130, v130, v94
	v_add_f32_e32 v131, v131, v95
	v_cvt_pk_bf16_f32 v127, v94, v95
	global_load_dwordx2 v[46:47], v133, s[12:13] offset:112
	v_add_u32_e32 v176, s70, v238
	ds_read_b64_tr_b16 v[144:145], v176 offset:8192
	ds_read_b64_tr_b16 v[146:147], v176 offset:9216
	ds_read_b64_tr_b16 v[148:149], v176 offset:8704
	ds_read_b64_tr_b16 v[150:151], v176 offset:9728
	ds_read_b64_tr_b16 v[152:153], v176 offset:10240
	ds_read_b64_tr_b16 v[154:155], v176 offset:11264
	ds_read_b64_tr_b16 v[156:157], v176 offset:10752
	ds_read_b64_tr_b16 v[158:159], v176 offset:11776
	ds_read_b64_tr_b16 v[160:161], v176 offset:12288
	ds_read_b64_tr_b16 v[162:163], v176 offset:13312
	ds_read_b64_tr_b16 v[164:165], v176 offset:12800
	ds_read_b64_tr_b16 v[166:167], v176 offset:13824
	s_waitcnt lgkmcnt(10)
	v_mfma_f32_32x32x16_bf16 v[0:15], v[144:147], v[112:115], v[0:15]
	ds_read_b64_tr_b16 v[168:169], v176 offset:14336
	ds_read_b64_tr_b16 v[170:171], v176 offset:15360
	s_waitcnt lgkmcnt(10)
	v_mfma_f32_32x32x16_bf16 v[16:31], v[148:151], v[112:115], v[16:31]
	ds_read_b64_tr_b16 v[172:173], v176 offset:14848
	ds_read_b64_tr_b16 v[174:175], v176 offset:15872
	s_waitcnt lgkmcnt(10)
	v_mfma_f32_32x32x16_bf16 v[0:15], v[152:155], v[116:119], v[0:15]
	s_waitcnt lgkmcnt(8)
	v_mfma_f32_32x32x16_bf16 v[16:31], v[156:159], v[116:119], v[16:31]
	s_waitcnt lgkmcnt(6)
	v_mfma_f32_32x32x16_bf16 v[0:15], v[160:163], v[120:123], v[0:15]
	s_waitcnt lgkmcnt(4)
	v_mfma_f32_32x32x16_bf16 v[16:31], v[164:167], v[120:123], v[16:31]
	s_waitcnt lgkmcnt(2)
	v_mfma_f32_32x32x16_bf16 v[0:15], v[168:171], v[124:127], v[0:15]
	s_waitcnt lgkmcnt(0)
	v_mfma_f32_32x32x16_bf16 v[16:31], v[172:175], v[124:127], v[16:31]
	s_mov_b32 s0, s64
	s_mov_b32 s64, s65
	s_mov_b32 s65, s68
	s_mov_b32 s68, s0
	s_mov_b32 s0, s69
	s_mov_b32 s69, s70
	s_mov_b32 s70, s71
	s_mov_b32 s71, s0
	s_waitcnt vmcnt(0)
	s_mov_b64 s[30:31], s[14:15]
	s_add_i32 s4, s4, s5
	s_mov_b32 s101, 0
	s_cmp_ge_i32 s4, s7
	s_cbranch_scc1 .Lat_dg_end
	s_cmp_ge_i32 s4, s6
	s_cbranch_scc1 .Lat_dg_ctx
	s_mul_i32 s0, s8, s6
	s_add_i32 s0, s0, s4
	s_mul_hi_u32 s1, s0, 0xaaaaaaab
	s_lshr_b32 s1, s1, 7
	s_mul_i32 s32, s1, 192
	s_sub_i32 s32, s0, s32
	s_lshr_b32 s56, s32, 4
	s_and_b32 s32, s32, 15
	s_lshl_b32 s76, s32, 8
	s_lshl_b32 s77, s1, 12
	s_add_i32 s77, s77, s76
	s_mov_b32 s78, 0
	s_mov_b32 s27, 32
	s_branch .Lat_dg_ptrs

.Lat_done:
	v_mov_b32_e32 v128, s26
	v_lshrrev_b32_e32 v132, 6, v143
	v_lshlrev_b32_e32 v132, 2, v132
	v_add_u32_e32 v132, 131072, v132
	ds_write_b32 v132, v128
	s_waitcnt lgkmcnt(0)
	s_barrier
	v_mov_b32_e32 v132, 131072
	ds_read_b128 v[48:51], v132
	ds_read_b128 v[52:55], v132 offset:16
	s_waitcnt lgkmcnt(0)
	v_or_b32_e32 v48, v48, v49
	v_or3_b32 v48, v48, v50, v51
	v_or3_b32 v48, v48, v52, v53
	v_or3_b32 v48, v48, v54, v55
	s_nop 0
	v_readfirstlane_b32 s26, v48
	s_mov_b64 exec, -1
